# Swiglu GEMMs: load the tile's row scales before the K loop (spare VGPRs) so the epilogue starts without a memory round trip
# speedup vs baseline: 1.0051x; 1.0011x over previous
; #define PG8_STAGE(bufoff, gbase, voff) do { _Pragma("unroll") for (int _i = 0; _i < 2; ++_i) \
;         __builtin_amdgcn_global_load_lds((const unsigned*)((const char*)(gbase) + (voff)[_i]), (LAS unsigned*)(lds + (bufoff) + ldsw + _i * 8192), 16, 0, 0); } while (0)
; #define PG8_LDA(dst, b, h) do { _Pragma("unroll") for (int m = 0; m < 4; ++m) _Pragma("unroll") for (int k = 0; k < 2; ++k) dst[m][k] = *(const LAS bf16x8*)(lds + PG8_SA(b, h) + aoff + m * 2048 + k * 1024); } while (0)
; #define PG8_LDB(dst, b, h) do { _Pragma("unroll") for (int n = 0; n < 2; ++n) _Pragma("unroll") for (int k = 0; k < 2; ++k) dst[n][k] = *(const LAS bf16x8*)(lds + PG8_SB(b, h) + boff + n * 2048 + k * 1024); } while (0)
; #define PG8_SCHED __builtin_amdgcn_sched_barrier(0)
; template <class Epi>
; __device__ __forceinline__ void gemm_phase(LAS unsigned char* lds, const Gemm g, const StaticOrder& S, const Epi& E) {
;     ...
;         const bool has_next = S.next(ui + 1, nxt);
;         const char* nA = has_next ? (const char*)g.A + (size_t)nxt.pm * tstep : cA; const char* nB = has_next ? (const char*)g.Bt + (size_t)nxt.pn * tstep : cB;
;         for (int t = 0; t < nt; t += 2) {
;             const bool last = (t == nt - 2);
;             const char* a1 = cA + (size_t)(t + 1) * kstep;
;             const char* a2 = last ? nA : cA + (size_t)(t + 2) * kstep; const char* b2 = last ? nB : cB + (size_t)(t + 2) * kstep;
;             const char* a3 = a2 + kstep; const char* b3 = b2 + kstep;
;             PG8_LDB(B0, 0, 0); PG8_SCHED; PG8_LDA(At, 0, 0); PG8_STAGE(PG8_SA(1, 1), a1 + hstep, voffA);
;     __device__ __forceinline__ void operator()(const f32x4 (&acc)[2][2][4][2], const Unit& u, int wr, int wc, int fr, int fq) const {
;     ...
;             for (int m = 0; m < 4; ++m) { bf16_t* rowp = O + (size_t)(row0 + ai * HALF + m * 16) * DFF + col0;
;                 const float r = rs[row0 + ai * HALF + m * 16], r2 = r * r;
.LBB0_202:
	s_ashr_i32 s25, s24, 31
	v_cmp_lt_i64_e32 vcc, s[26:27], v[140:141]
	s_lshl_b64 s[26:27], s[24:25], 20
	s_add_u32 s26, s97, s26
	s_addc_u32 s27, s94, s27
	s_and_b64 s[28:29], vcc, exec
	s_cselect_b32 s25, s27, s43
	s_cselect_b32 s50, s26, s42
	s_ashr_i32 s23, s22, 31
	s_lshl_b64 s[28:29], s[22:23], 20
	s_add_u32 s28, s16, s28
	s_addc_u32 s29, s17, s29
	s_and_b64 s[46:47], vcc, exec
	s_cselect_b32 s23, s29, s45
	s_cselect_b32 s51, s28, s44
	s_add_u32 s42, s42, 0x80080
	s_addc_u32 s43, s43, 0
	s_add_u32 s52, s44, 0x100
	v_mov_b32_e32 v0, 0
	s_addc_u32 s53, s45, 0
	s_mov_b32 s54, -2
	v_mov_b32_e32 v1, v0
	v_mov_b32_e32 v2, v0
	v_mov_b32_e32 v3, v0
	v_mov_b32_e32 v4, v0
	v_mov_b32_e32 v5, v0
	v_mov_b32_e32 v6, v0
	v_mov_b32_e32 v7, v0
	v_mov_b32_e32 v16, v0
	v_mov_b32_e32 v17, v0
	v_mov_b32_e32 v18, v0
	v_mov_b32_e32 v19, v0
	v_mov_b32_e32 v20, v0
	v_mov_b32_e32 v21, v0
	v_mov_b32_e32 v22, v0
	v_mov_b32_e32 v23, v0
	v_mov_b32_e32 v32, v0
	v_mov_b32_e32 v33, v0
	v_mov_b32_e32 v34, v0
	v_mov_b32_e32 v35, v0
	v_mov_b32_e32 v36, v0
	v_mov_b32_e32 v37, v0
	v_mov_b32_e32 v38, v0
	v_mov_b32_e32 v39, v0
	v_mov_b32_e32 v48, v0
	v_mov_b32_e32 v49, v0
	v_mov_b32_e32 v50, v0
	v_mov_b32_e32 v51, v0
	v_mov_b32_e32 v52, v0
	v_mov_b32_e32 v53, v0
	v_mov_b32_e32 v54, v0
	v_mov_b32_e32 v55, v0
	v_mov_b32_e32 v8, v0
	v_mov_b32_e32 v9, v0
	v_mov_b32_e32 v10, v0
	v_mov_b32_e32 v11, v0
	v_mov_b32_e32 v12, v0
	v_mov_b32_e32 v13, v0
	v_mov_b32_e32 v14, v0
	v_mov_b32_e32 v15, v0
	v_mov_b32_e32 v24, v0
	v_mov_b32_e32 v25, v0
	v_mov_b32_e32 v26, v0
	v_mov_b32_e32 v27, v0
	v_mov_b32_e32 v28, v0
	v_mov_b32_e32 v29, v0
	v_mov_b32_e32 v30, v0
	v_mov_b32_e32 v31, v0
	v_mov_b32_e32 v40, v0
	v_mov_b32_e32 v41, v0
	v_mov_b32_e32 v42, v0
	v_mov_b32_e32 v43, v0
	v_mov_b32_e32 v44, v0
	v_mov_b32_e32 v45, v0
	v_mov_b32_e32 v46, v0
	v_mov_b32_e32 v47, v0
	v_mov_b32_e32 v56, v0
	v_mov_b32_e32 v57, v0
	v_mov_b32_e32 v58, v0
	v_mov_b32_e32 v59, v0
	v_mov_b32_e32 v60, v0
	v_mov_b32_e32 v61, v0
	v_mov_b32_e32 v62, v0
	v_mov_b32_e32 v63, v0
	v_mov_b32_e32 v64, v0
	v_mov_b32_e32 v65, v0
	v_mov_b32_e32 v66, v0
	v_mov_b32_e32 v67, v0
	v_mov_b32_e32 v68, v0
	v_mov_b32_e32 v69, v0
	v_mov_b32_e32 v70, v0
	v_mov_b32_e32 v71, v0
	v_mov_b32_e32 v80, v0
	v_mov_b32_e32 v81, v0
	v_mov_b32_e32 v82, v0
	v_mov_b32_e32 v83, v0
	v_mov_b32_e32 v84, v0
	v_mov_b32_e32 v85, v0
	v_mov_b32_e32 v86, v0
	v_mov_b32_e32 v87, v0
	v_mov_b32_e32 v96, v0
	v_mov_b32_e32 v97, v0
	v_mov_b32_e32 v98, v0
	v_mov_b32_e32 v99, v0
	v_mov_b32_e32 v100, v0
	v_mov_b32_e32 v101, v0
	v_mov_b32_e32 v102, v0
	v_mov_b32_e32 v103, v0
	v_mov_b32_e32 v112, v0
	v_mov_b32_e32 v113, v0
	v_mov_b32_e32 v114, v0
	v_mov_b32_e32 v115, v0
	v_mov_b32_e32 v116, v0
	v_mov_b32_e32 v117, v0
	v_mov_b32_e32 v118, v0
	v_mov_b32_e32 v119, v0
	v_mov_b32_e32 v72, v0
	v_mov_b32_e32 v73, v0
	v_mov_b32_e32 v74, v0
	v_mov_b32_e32 v75, v0
	v_mov_b32_e32 v76, v0
	v_mov_b32_e32 v77, v0
	v_mov_b32_e32 v78, v0
	v_mov_b32_e32 v79, v0
	v_mov_b32_e32 v88, v0
	v_mov_b32_e32 v89, v0
	v_mov_b32_e32 v90, v0
	v_mov_b32_e32 v91, v0
	v_mov_b32_e32 v92, v0
	v_mov_b32_e32 v93, v0
	v_mov_b32_e32 v94, v0
	v_mov_b32_e32 v95, v0
	v_mov_b32_e32 v104, v0
	v_mov_b32_e32 v105, v0
	v_mov_b32_e32 v106, v0
	v_mov_b32_e32 v107, v0
	v_mov_b32_e32 v108, v0
	v_mov_b32_e32 v109, v0
	v_mov_b32_e32 v110, v0
	v_mov_b32_e32 v111, v0
	v_mov_b32_e32 v120, v0
	v_mov_b32_e32 v121, v0
	v_mov_b32_e32 v122, v0
	v_mov_b32_e32 v123, v0
	v_mov_b32_e32 v124, v0
	v_mov_b32_e32 v125, v0
	v_mov_b32_e32 v126, v0
	v_mov_b32_e32 v127, v0
	v_lshl_add_u32 v144, s40, 8, v150
	v_ashrrev_i32_e32 v145, 31, v144
	v_lshl_add_u64 v[148:149], v[144:145], 2, s[14:15]
	global_load_dword v224, v[148:149], off
	global_load_dword v225, v[148:149], off offset:64
	global_load_dword v226, v[148:149], off offset:128
	global_load_dword v227, v[148:149], off offset:192
	global_load_dword v228, v[148:149], off offset:512
	global_load_dword v229, v[148:149], off offset:576
	global_load_dword v230, v[148:149], off offset:640
	global_load_dword v231, v[148:149], off offset:704
.LBB0_203:
	ds_read_b128 v[144:147], v153
	ds_read_b128 v[160:163], v153 offset:1024
	ds_read_b128 v[164:167], v153 offset:2048
	ds_read_b128 v[168:171], v153 offset:3072
	s_add_u32 s44, s42, 0xfff80080
	s_addc_u32 s45, s43, -1
	s_cmp_eq_u32 s54, 28
	s_cselect_b32 s47, s25, s45
	s_cselect_b32 s46, s50, s44
	s_cselect_b32 s45, s23, s53
	s_cselect_b32 s44, s51, s52
	v_lshl_add_u64 v[148:149], s[42:43], 0, v[136:137]
	s_add_i32 m0, s11, 0xc000
	ds_read_b128 v[172:175], v154
	ds_read_b128 v[176:179], v154 offset:1024
	ds_read_b128 v[180:183], v154 offset:2048
	ds_read_b128 v[184:187], v154 offset:3072
	ds_read_b128 v[188:191], v154 offset:4096
	ds_read_b128 v[192:195], v154 offset:5120
	ds_read_b128 v[196:199], v154 offset:6144
	ds_read_b128 v[200:203], v154 offset:7168
	global_load_lds_dwordx4 v[148:149], off
	v_lshl_add_u64 v[148:149], s[42:43], 0, v[138:139]
	s_add_i32 m0, s11, 0xe000
	s_nop 0
	global_load_lds_dwordx4 v[148:149], off
	s_waitcnt lgkmcnt(8)
	s_barrier
; #define PG8_STAGE(bufoff, gbase, voff) do { _Pragma("unroll") for (int _i = 0; _i < 2; ++_i) \
;         __builtin_amdgcn_global_load_lds((const unsigned*)((const char*)(gbase) + (voff)[_i]), (LAS unsigned*)(lds + (bufoff) + ldsw + _i * 8192), 16, 0, 0); } while (0)
; #define PG8_LDA(dst, b, h) do { _Pragma("unroll") for (int m = 0; m < 4; ++m) _Pragma("unroll") for (int k = 0; k < 2; ++k) dst[m][k] = *(const LAS bf16x8*)(lds + PG8_SA(b, h) + aoff + m * 2048 + k * 1024); } while (0)
; #define PG8_LDB(dst, b, h) do { _Pragma("unroll") for (int n = 0; n < 2; ++n) _Pragma("unroll") for (int k = 0; k < 2; ++k) dst[n][k] = *(const LAS bf16x8*)(lds + PG8_SB(b, h) + boff + n * 2048 + k * 1024); } while (0)
; #define PG8_MMA(ai, bj, At, Bt) do { __builtin_amdgcn_s_setprio(1); _Pragma("unroll") for (int m = 0; m < 4; ++m) _Pragma("unroll") for (int n = 0; n < 2; ++n) _Pragma("unroll") for (int k = 0; k < 2; ++k) \
;         acc[ai][bj][m][n] = __builtin_amdgcn_mfma_f32_16x16x32_bf16(Bt[n][k], At[m][k], acc[ai][bj][m][n], 0, 0, 0); __builtin_amdgcn_s_setprio(0); } while (0)
; #define PG8_WAIT_V(n) asm volatile("s_waitcnt vmcnt(" #n ")" ::: "memory")
; #define PG8_WAIT_L(n) asm volatile("s_waitcnt lgkmcnt(" #n ")" ::: "memory")
; #define PG8_BAR __builtin_amdgcn_s_barrier()
; #define PG8_SCHED __builtin_amdgcn_sched_barrier(0)
; template <class Epi>
; __device__ __forceinline__ void gemm_phase(LAS unsigned char* lds, const Gemm g, const StaticOrder& S, const Epi& E) {
;     ...
;             PG8_LDB(B0, 0, 0); PG8_SCHED; PG8_LDA(At, 0, 0); PG8_STAGE(PG8_SA(1, 1), a1 + hstep, voffA);
;             PG8_WAIT_L(8); PG8_BAR; PG8_WAIT_L(0); PG8_MMA(0, 0, At, B0); PG8_BAR; PG8_SCHED;
;             PG8_LDB(B1, 0, 1); PG8_STAGE(PG8_SB(0, 0), b2, voffB);
;             PG8_BAR; PG8_WAIT_L(0); PG8_MMA(0, 1, At, B1); PG8_BAR;
;             PG8_LDA(At, 0, 1); PG8_STAGE(PG8_SA(0, 0), a2, voffA);
;             PG8_BAR; PG8_WAIT_L(0); PG8_MMA(1, 0, At, B0); PG8_BAR; PG8_SCHED;
;             PG8_STAGE(PG8_SB(0, 1), b2 + hstep, voffB);
;             PG8_WAIT_V(6); PG8_BAR; PG8_MMA(1, 1, At, B1); PG8_BAR;
	s_waitcnt lgkmcnt(0)
	s_setprio 1
	s_waitcnt lgkmcnt(0)
	v_mfma_f32_16x16x32_bf16 v[124:127], v[144:147], v[172:175], v[124:127]
	v_mfma_f32_16x16x32_bf16 v[120:123], v[164:167], v[172:175], v[120:123]
	v_mfma_f32_16x16x32_bf16 v[108:111], v[144:147], v[180:183], v[108:111]
	v_mfma_f32_16x16x32_bf16 v[104:107], v[164:167], v[180:183], v[104:107]
	v_mfma_f32_16x16x32_bf16 v[92:95], v[144:147], v[188:191], v[92:95]
	v_mfma_f32_16x16x32_bf16 v[88:91], v[164:167], v[188:191], v[88:91]
	v_mfma_f32_16x16x32_bf16 v[76:79], v[144:147], v[196:199], v[76:79]
	v_mfma_f32_16x16x32_bf16 v[72:75], v[164:167], v[196:199], v[72:75]
	v_mfma_f32_16x16x32_bf16 v[124:127], v[160:163], v[176:179], v[124:127]
	v_mfma_f32_16x16x32_bf16 v[120:123], v[168:171], v[176:179], v[120:123]
	v_mfma_f32_16x16x32_bf16 v[108:111], v[160:163], v[184:187], v[108:111]
	v_mfma_f32_16x16x32_bf16 v[104:107], v[168:171], v[184:187], v[104:107]
	v_mfma_f32_16x16x32_bf16 v[92:95], v[160:163], v[192:195], v[92:95]
	v_mfma_f32_16x16x32_bf16 v[88:91], v[168:171], v[192:195], v[88:91]
	v_mfma_f32_16x16x32_bf16 v[76:79], v[160:163], v[200:203], v[76:79]
	v_mfma_f32_16x16x32_bf16 v[72:75], v[168:171], v[200:203], v[72:75]
	s_setprio 0
	s_barrier
	s_add_i32 s55, s41, s10
	v_lshl_add_u64 v[148:149], s[44:45], 0, v[132:133]
	s_mov_b32 m0, s55
	ds_read_b128 v[204:207], v155
	ds_read_b128 v[208:211], v155 offset:1024
	ds_read_b128 v[212:215], v155 offset:2048
	ds_read_b128 v[216:219], v155 offset:3072
	global_load_lds_dwordx4 v[148:149], off
	v_lshl_add_u64 v[156:157], s[44:45], 0, v[128:129]
	s_add_i32 m0, s55, 0x2000
	s_nop 0
	global_load_lds_dwordx4 v[156:157], off
	s_barrier
	s_waitcnt lgkmcnt(0)
	s_setprio 1
	s_waitcnt lgkmcnt(0)
	v_mfma_f32_16x16x32_bf16 v[116:119], v[204:207], v[172:175], v[116:119]
	v_mfma_f32_16x16x32_bf16 v[112:115], v[212:215], v[172:175], v[112:115]
	v_mfma_f32_16x16x32_bf16 v[100:103], v[204:207], v[180:183], v[100:103]
	v_mfma_f32_16x16x32_bf16 v[96:99], v[212:215], v[180:183], v[96:99]
	v_mfma_f32_16x16x32_bf16 v[84:87], v[204:207], v[188:191], v[84:87]
	v_mfma_f32_16x16x32_bf16 v[80:83], v[212:215], v[188:191], v[80:83]
	v_mfma_f32_16x16x32_bf16 v[68:71], v[204:207], v[196:199], v[68:71]
	v_mfma_f32_16x16x32_bf16 v[64:67], v[212:215], v[196:199], v[64:67]
	v_mfma_f32_16x16x32_bf16 v[116:119], v[208:211], v[176:179], v[116:119]
	v_mfma_f32_16x16x32_bf16 v[112:115], v[216:219], v[176:179], v[112:115]
	v_mfma_f32_16x16x32_bf16 v[100:103], v[208:211], v[184:187], v[100:103]
	v_mfma_f32_16x16x32_bf16 v[96:99], v[216:219], v[184:187], v[96:99]
	v_mfma_f32_16x16x32_bf16 v[84:87], v[208:211], v[192:195], v[84:87]
	v_mfma_f32_16x16x32_bf16 v[80:83], v[216:219], v[192:195], v[80:83]
	v_mfma_f32_16x16x32_bf16 v[68:71], v[208:211], v[200:203], v[68:71]
	v_mfma_f32_16x16x32_bf16 v[64:67], v[216:219], v[200:203], v[64:67]
	s_setprio 0
	s_mov_b32 m0, s11
	v_lshl_add_u64 v[220:221], s[46:47], 0, v[134:135]
	s_barrier
	ds_read_b128 v[172:175], v154 offset:16384
	ds_read_b128 v[176:179], v154 offset:17408
	ds_read_b128 v[180:183], v154 offset:18432
	ds_read_b128 v[184:187], v154 offset:19456
	ds_read_b128 v[188:191], v154 offset:20480
	ds_read_b128 v[192:195], v154 offset:21504
	ds_read_b128 v[196:199], v154 offset:22528
	ds_read_b128 v[200:203], v154 offset:23552
	global_load_lds_dwordx4 v[220:221], off
	v_lshl_add_u64 v[222:223], s[46:47], 0, v[130:131]
	s_mov_b32 m0, s13
	s_nop 0
	global_load_lds_dwordx4 v[222:223], off
	s_barrier
	s_waitcnt lgkmcnt(0)
	s_setprio 1
	s_waitcnt lgkmcnt(0)
	v_mfma_f32_16x16x32_bf16 v[60:63], v[144:147], v[172:175], v[60:63]
	v_mfma_f32_16x16x32_bf16 v[56:59], v[164:167], v[172:175], v[56:59]
	v_mfma_f32_16x16x32_bf16 v[44:47], v[144:147], v[180:183], v[44:47]
	v_mfma_f32_16x16x32_bf16 v[40:43], v[164:167], v[180:183], v[40:43]
	v_mfma_f32_16x16x32_bf16 v[28:31], v[144:147], v[188:191], v[28:31]
	v_mfma_f32_16x16x32_bf16 v[24:27], v[164:167], v[188:191], v[24:27]
	v_mfma_f32_16x16x32_bf16 v[12:15], v[144:147], v[196:199], v[12:15]
	v_mfma_f32_16x16x32_bf16 v[8:11], v[164:167], v[196:199], v[8:11]
	v_mfma_f32_16x16x32_bf16 v[60:63], v[160:163], v[176:179], v[60:63]
	v_mfma_f32_16x16x32_bf16 v[56:59], v[168:171], v[176:179], v[56:59]
	v_mfma_f32_16x16x32_bf16 v[44:47], v[160:163], v[184:187], v[44:47]
	v_mfma_f32_16x16x32_bf16 v[40:43], v[168:171], v[184:187], v[40:43]
	v_mfma_f32_16x16x32_bf16 v[28:31], v[160:163], v[192:195], v[28:31]
	v_mfma_f32_16x16x32_bf16 v[24:27], v[168:171], v[192:195], v[24:27]
	v_mfma_f32_16x16x32_bf16 v[12:15], v[160:163], v[200:203], v[12:15]
	v_mfma_f32_16x16x32_bf16 v[8:11], v[168:171], v[200:203], v[8:11]
	s_setprio 0
	s_barrier
	s_add_u32 s56, s44, 0x80000
	s_addc_u32 s57, s45, 0
	s_add_i32 s55, s48, s10
	v_lshl_add_u64 v[144:145], s[56:57], 0, v[132:133]
	s_mov_b32 m0, s55
	s_nop 0
	global_load_lds_dwordx4 v[144:145], off
	v_lshl_add_u64 v[144:145], s[56:57], 0, v[128:129]
	s_add_i32 m0, s55, 0x2000
	s_nop 0
	global_load_lds_dwordx4 v[144:145], off
	s_waitcnt vmcnt(6)
	s_barrier
	s_setprio 1
	v_mfma_f32_16x16x32_bf16 v[52:55], v[204:207], v[172:175], v[52:55]
	v_mfma_f32_16x16x32_bf16 v[48:51], v[212:215], v[172:175], v[48:51]
	v_mfma_f32_16x16x32_bf16 v[36:39], v[204:207], v[180:183], v[36:39]
	v_mfma_f32_16x16x32_bf16 v[32:35], v[212:215], v[180:183], v[32:35]
	v_mfma_f32_16x16x32_bf16 v[20:23], v[204:207], v[188:191], v[20:23]
	v_mfma_f32_16x16x32_bf16 v[16:19], v[212:215], v[188:191], v[16:19]
	v_mfma_f32_16x16x32_bf16 v[4:7], v[204:207], v[196:199], v[4:7]
	v_mfma_f32_16x16x32_bf16 v[0:3], v[212:215], v[196:199], v[0:3]
	v_mfma_f32_16x16x32_bf16 v[52:55], v[208:211], v[176:179], v[52:55]
	v_mfma_f32_16x16x32_bf16 v[48:51], v[216:219], v[176:179], v[48:51]
	v_mfma_f32_16x16x32_bf16 v[36:39], v[208:211], v[184:187], v[36:39]
	v_mfma_f32_16x16x32_bf16 v[32:35], v[216:219], v[184:187], v[32:35]
	v_mfma_f32_16x16x32_bf16 v[20:23], v[208:211], v[192:195], v[20:23]
	v_mfma_f32_16x16x32_bf16 v[16:19], v[216:219], v[192:195], v[16:19]
	v_mfma_f32_16x16x32_bf16 v[4:7], v[208:211], v[200:203], v[4:7]
	v_mfma_f32_16x16x32_bf16 v[0:3], v[216:219], v[200:203], v[0:3]
	s_setprio 0
	s_add_i32 s55, 0, 0x18000
	v_add_u32_e32 v168, s55, v151
	s_barrier
; #define PG8_STAGE(bufoff, gbase, voff) do { _Pragma("unroll") for (int _i = 0; _i < 2; ++_i) \
;         __builtin_amdgcn_global_load_lds((const unsigned*)((const char*)(gbase) + (voff)[_i]), (LAS unsigned*)(lds + (bufoff) + ldsw + _i * 8192), 16, 0, 0); } while (0)
; #define PG8_LDA(dst, b, h) do { _Pragma("unroll") for (int m = 0; m < 4; ++m) _Pragma("unroll") for (int k = 0; k < 2; ++k) dst[m][k] = *(const LAS bf16x8*)(lds + PG8_SA(b, h) + aoff + m * 2048 + k * 1024); } while (0)
; #define PG8_LDB(dst, b, h) do { _Pragma("unroll") for (int n = 0; n < 2; ++n) _Pragma("unroll") for (int k = 0; k < 2; ++k) dst[n][k] = *(const LAS bf16x8*)(lds + PG8_SB(b, h) + boff + n * 2048 + k * 1024); } while (0)
; #define PG8_MMA(ai, bj, At, Bt) do { __builtin_amdgcn_s_setprio(1); _Pragma("unroll") for (int m = 0; m < 4; ++m) _Pragma("unroll") for (int n = 0; n < 2; ++n) _Pragma("unroll") for (int k = 0; k < 2; ++k) \
;         acc[ai][bj][m][n] = __builtin_amdgcn_mfma_f32_16x16x32_bf16(Bt[n][k], At[m][k], acc[ai][bj][m][n], 0, 0, 0); __builtin_amdgcn_s_setprio(0); } while (0)
; #define PG8_WAIT_V(n) asm volatile("s_waitcnt vmcnt(" #n ")" ::: "memory")
; #define PG8_WAIT_L(n) asm volatile("s_waitcnt lgkmcnt(" #n ")" ::: "memory")
; #define PG8_BAR __builtin_amdgcn_s_barrier()
; #define PG8_SCHED __builtin_amdgcn_sched_barrier(0)
; template <class Epi>
; __device__ __forceinline__ void gemm_phase(LAS unsigned char* lds, const Gemm g, const StaticOrder& S, const Epi& E) {
;     ...
;             PG8_LDB(B0, 1, 0); PG8_SCHED; PG8_LDA(At, 1, 0); PG8_STAGE(PG8_SA(0, 1), a2 + hstep, voffA);
;             PG8_WAIT_L(8); PG8_BAR; PG8_WAIT_L(0); PG8_MMA(0, 0, At, B0); PG8_BAR; PG8_SCHED;
;             PG8_LDB(B1, 1, 1); PG8_STAGE(PG8_SB(1, 0), b3, voffB);
;             PG8_BAR; PG8_WAIT_L(0); PG8_MMA(0, 1, At, B1); PG8_BAR;
;             PG8_LDA(At, 1, 1); PG8_STAGE(PG8_SA(1, 0), a3, voffA);
;             PG8_BAR; PG8_WAIT_L(0); PG8_MMA(1, 0, At, B0); PG8_BAR; PG8_SCHED;
;             PG8_STAGE(PG8_SB(1, 1), b3 + hstep, voffB);
;             PG8_WAIT_V(6); PG8_BAR; PG8_MMA(1, 1, At, B1); PG8_BAR;
	ds_read_b128 v[144:147], v168
	ds_read_b128 v[160:163], v168 offset:1024
	ds_read_b128 v[164:167], v168 offset:2048
	ds_read_b128 v[168:171], v168 offset:3072
	s_add_u32 s46, s46, 0x80000
	s_addc_u32 s47, s47, 0
	s_mov_b32 m0, s30
	v_lshl_add_u64 v[204:205], s[46:47], 0, v[134:135]
	ds_read_b128 v[172:175], v154 offset:32768
	ds_read_b128 v[176:179], v154 offset:33792
	ds_read_b128 v[180:183], v154 offset:34816
	ds_read_b128 v[184:187], v154 offset:35840
	ds_read_b128 v[188:191], v154 offset:36864
	ds_read_b128 v[192:195], v154 offset:37888
	ds_read_b128 v[196:199], v154 offset:38912
	ds_read_b128 v[200:203], v154 offset:39936
	global_load_lds_dwordx4 v[204:205], off
	v_lshl_add_u64 v[204:205], s[46:47], 0, v[130:131]
	s_mov_b32 m0, s31
	s_nop 0
	global_load_lds_dwordx4 v[204:205], off
	s_waitcnt lgkmcnt(8)
	s_barrier
	s_waitcnt lgkmcnt(0)
	s_setprio 1
	s_waitcnt lgkmcnt(0)
	v_mfma_f32_16x16x32_bf16 v[124:127], v[144:147], v[172:175], v[124:127]
	v_mfma_f32_16x16x32_bf16 v[120:123], v[164:167], v[172:175], v[120:123]
	v_mfma_f32_16x16x32_bf16 v[108:111], v[144:147], v[180:183], v[108:111]
	v_mfma_f32_16x16x32_bf16 v[104:107], v[164:167], v[180:183], v[104:107]
	v_mfma_f32_16x16x32_bf16 v[92:95], v[144:147], v[188:191], v[92:95]
	v_mfma_f32_16x16x32_bf16 v[88:91], v[164:167], v[188:191], v[88:91]
	v_mfma_f32_16x16x32_bf16 v[76:79], v[144:147], v[196:199], v[76:79]
	v_mfma_f32_16x16x32_bf16 v[72:75], v[164:167], v[196:199], v[72:75]
	v_mfma_f32_16x16x32_bf16 v[124:127], v[160:163], v[176:179], v[124:127]
	v_mfma_f32_16x16x32_bf16 v[120:123], v[168:171], v[176:179], v[120:123]
	v_mfma_f32_16x16x32_bf16 v[108:111], v[160:163], v[184:187], v[108:111]
	v_mfma_f32_16x16x32_bf16 v[104:107], v[168:171], v[184:187], v[104:107]
	v_mfma_f32_16x16x32_bf16 v[92:95], v[160:163], v[192:195], v[92:95]
	v_mfma_f32_16x16x32_bf16 v[88:91], v[168:171], v[192:195], v[88:91]
	v_mfma_f32_16x16x32_bf16 v[76:79], v[160:163], v[200:203], v[76:79]
	v_mfma_f32_16x16x32_bf16 v[72:75], v[168:171], v[200:203], v[72:75]
	s_setprio 0
	s_barrier
	s_add_i32 s46, 0, 0x1c000
	s_add_i32 s47, s55, s10
	v_add_u32_e32 v216, s46, v151
	v_lshl_add_u64 v[148:149], v[148:149], 0, s[8:9]
	s_mov_b32 m0, s47
	ds_read_b128 v[204:207], v216
	ds_read_b128 v[208:211], v216 offset:1024
	ds_read_b128 v[212:215], v216 offset:2048
	ds_read_b128 v[216:219], v216 offset:3072
	global_load_lds_dwordx4 v[148:149], off
	v_lshl_add_u64 v[148:149], v[156:157], 0, s[8:9]
	s_add_i32 m0, s47, 0x2000
	s_nop 0
	global_load_lds_dwordx4 v[148:149], off
	s_barrier
	s_waitcnt lgkmcnt(0)
	s_setprio 1
	s_waitcnt lgkmcnt(0)
	v_mfma_f32_16x16x32_bf16 v[116:119], v[204:207], v[172:175], v[116:119]
	v_mfma_f32_16x16x32_bf16 v[112:115], v[212:215], v[172:175], v[112:115]
	v_mfma_f32_16x16x32_bf16 v[100:103], v[204:207], v[180:183], v[100:103]
	v_mfma_f32_16x16x32_bf16 v[96:99], v[212:215], v[180:183], v[96:99]
	v_mfma_f32_16x16x32_bf16 v[84:87], v[204:207], v[188:191], v[84:87]
	v_mfma_f32_16x16x32_bf16 v[80:83], v[212:215], v[188:191], v[80:83]
	v_mfma_f32_16x16x32_bf16 v[68:71], v[204:207], v[196:199], v[68:71]
	v_mfma_f32_16x16x32_bf16 v[64:67], v[212:215], v[196:199], v[64:67]
	v_mfma_f32_16x16x32_bf16 v[116:119], v[208:211], v[176:179], v[116:119]
	v_mfma_f32_16x16x32_bf16 v[112:115], v[216:219], v[176:179], v[112:115]
	v_mfma_f32_16x16x32_bf16 v[100:103], v[208:211], v[184:187], v[100:103]
	v_mfma_f32_16x16x32_bf16 v[96:99], v[216:219], v[184:187], v[96:99]
	v_mfma_f32_16x16x32_bf16 v[84:87], v[208:211], v[192:195], v[84:87]
	v_mfma_f32_16x16x32_bf16 v[80:83], v[216:219], v[192:195], v[80:83]
	v_mfma_f32_16x16x32_bf16 v[68:71], v[208:211], v[200:203], v[68:71]
	v_mfma_f32_16x16x32_bf16 v[64:67], v[216:219], v[200:203], v[64:67]
	s_setprio 0
	s_mov_b32 m0, s36
	v_lshl_add_u64 v[148:149], v[220:221], 0, s[8:9]
	s_barrier
	ds_read_b128 v[172:175], v154 offset:49152
	ds_read_b128 v[176:179], v154 offset:50176
	ds_read_b128 v[180:183], v154 offset:51200
	ds_read_b128 v[184:187], v154 offset:52224
	ds_read_b128 v[188:191], v154 offset:53248
	ds_read_b128 v[192:195], v154 offset:54272
	ds_read_b128 v[196:199], v154 offset:55296
	ds_read_b128 v[200:203], v154 offset:56320
	global_load_lds_dwordx4 v[148:149], off
	v_lshl_add_u64 v[148:149], v[222:223], 0, s[8:9]
	s_mov_b32 m0, s37
	s_nop 0
	global_load_lds_dwordx4 v[148:149], off
	s_barrier
	s_waitcnt lgkmcnt(0)
	s_setprio 1
	s_waitcnt lgkmcnt(0)
	v_mfma_f32_16x16x32_bf16 v[60:63], v[144:147], v[172:175], v[60:63]
	v_mfma_f32_16x16x32_bf16 v[56:59], v[164:167], v[172:175], v[56:59]
	v_mfma_f32_16x16x32_bf16 v[44:47], v[144:147], v[180:183], v[44:47]
	v_mfma_f32_16x16x32_bf16 v[40:43], v[164:167], v[180:183], v[40:43]
	v_mfma_f32_16x16x32_bf16 v[28:31], v[144:147], v[188:191], v[28:31]
	v_mfma_f32_16x16x32_bf16 v[24:27], v[164:167], v[188:191], v[24:27]
	v_mfma_f32_16x16x32_bf16 v[12:15], v[144:147], v[196:199], v[12:15]
	v_mfma_f32_16x16x32_bf16 v[8:11], v[164:167], v[196:199], v[8:11]
	v_mfma_f32_16x16x32_bf16 v[60:63], v[160:163], v[176:179], v[60:63]
	v_mfma_f32_16x16x32_bf16 v[56:59], v[168:171], v[176:179], v[56:59]
	v_mfma_f32_16x16x32_bf16 v[44:47], v[160:163], v[184:187], v[44:47]
	v_mfma_f32_16x16x32_bf16 v[40:43], v[168:171], v[184:187], v[40:43]
	v_mfma_f32_16x16x32_bf16 v[28:31], v[160:163], v[192:195], v[28:31]
	v_mfma_f32_16x16x32_bf16 v[24:27], v[168:171], v[192:195], v[24:27]
	v_mfma_f32_16x16x32_bf16 v[12:15], v[160:163], v[200:203], v[12:15]
	v_mfma_f32_16x16x32_bf16 v[8:11], v[168:171], v[200:203], v[8:11]
	s_setprio 0
	s_barrier
; __device__ __forceinline__ float fast_rcp(float x) { return __builtin_amdgcn_rcpf(x); }
; __device__ __forceinline__ float fast_exp2(float x) { return __builtin_amdgcn_exp2f(x); }
; #define PG8_MMA(ai, bj, At, Bt) do { __builtin_amdgcn_s_setprio(1); _Pragma("unroll") for (int m = 0; m < 4; ++m) _Pragma("unroll") for (int n = 0; n < 2; ++n) _Pragma("unroll") for (int k = 0; k < 2; ++k) \
;         acc[ai][bj][m][n] = __builtin_amdgcn_mfma_f32_16x16x32_bf16(Bt[n][k], At[m][k], acc[ai][bj][m][n], 0, 0, 0); __builtin_amdgcn_s_setprio(0); } while (0)
; #define PG8_WAIT_V(n) asm volatile("s_waitcnt vmcnt(" #n ")" ::: "memory")
; #define PG8_BAR __builtin_amdgcn_s_barrier()
; __device__ __forceinline__ u32x4 pack8(f32x4 v0, f32x4 v1) { u32x4 w; w.x = cvt_pk_bf16(v0[0], v0[1]); w.y = cvt_pk_bf16(v0[2], v0[3]); w.z = cvt_pk_bf16(v1[0], v1[1]); w.w = cvt_pk_bf16(v1[2], v1[3]); return w; }
; template <class Epi>
; __device__ __forceinline__ void gemm_phase(LAS unsigned char* lds, const Gemm g, const StaticOrder& S, const Epi& E) {
;     ...
;             PG8_WAIT_V(6); PG8_BAR; PG8_MMA(1, 1, At, B1); PG8_BAR;
;         }
;         E(acc, cur, wr, wc, fr, fq);
;     __device__ __forceinline__ void operator()(const f32x4 (&acc)[2][2][4][2], const Unit& u, int wr, int wc, int fr, int fq) const {
;         const int row0 = u.pm * BM + wr * 64 + fr, col0 = u.pn * HALF + wc * 32 + 8 * fq;
; #pragma unroll
;         for (int ai = 0; ai < 2; ++ai)
; #pragma unroll
;             for (int m = 0; m < 4; ++m) { bf16_t* rowp = O + (size_t)(row0 + ai * HALF + m * 16) * DFF + col0;
;                 const float r = rs[row0 + ai * HALF + m * 16], r2 = r * r;
;                 f32x4 h0, h1;
; #pragma unroll
;                 for (int j = 0; j < 4; ++j) {
;                     const float g0 = acc[ai][0][m][0][j], g1 = acc[ai][0][m][1][j];
;                     h0[j] = g0 * r2 * fast_rcp(1.0f + fast_exp2(g0 * (-LOG2E * r))) * acc[ai][1][m][0][j];
;                     h1[j] = g1 * r2 * fast_rcp(1.0f + fast_exp2(g1 * (-LOG2E * r))) * acc[ai][1][m][1][j]; }
;                 *(u32x4*)rowp = pack8(h0, h1); }
	s_add_u32 s44, s44, 0x80080
	s_addc_u32 s45, s45, 0
	s_add_i32 s46, s46, s10
	v_lshl_add_u64 v[144:145], s[44:45], 0, v[132:133]
	s_mov_b32 m0, s46
	s_nop 0
	global_load_lds_dwordx4 v[144:145], off
	v_lshl_add_u64 v[144:145], s[44:45], 0, v[128:129]
	s_add_i32 m0, s46, 0x2000
	s_nop 0
	global_load_lds_dwordx4 v[144:145], off
	s_waitcnt vmcnt(6)
	s_barrier
	s_setprio 1
	v_mfma_f32_16x16x32_bf16 v[52:55], v[204:207], v[172:175], v[52:55]
	v_mfma_f32_16x16x32_bf16 v[48:51], v[212:215], v[172:175], v[48:51]
	v_mfma_f32_16x16x32_bf16 v[36:39], v[204:207], v[180:183], v[36:39]
	v_mfma_f32_16x16x32_bf16 v[32:35], v[212:215], v[180:183], v[32:35]
	v_mfma_f32_16x16x32_bf16 v[20:23], v[204:207], v[188:191], v[20:23]
	v_mfma_f32_16x16x32_bf16 v[16:19], v[212:215], v[188:191], v[16:19]
	v_mfma_f32_16x16x32_bf16 v[4:7], v[204:207], v[196:199], v[4:7]
	v_mfma_f32_16x16x32_bf16 v[0:3], v[212:215], v[196:199], v[0:3]
	v_mfma_f32_16x16x32_bf16 v[52:55], v[208:211], v[176:179], v[52:55]
	v_mfma_f32_16x16x32_bf16 v[48:51], v[216:219], v[176:179], v[48:51]
	v_mfma_f32_16x16x32_bf16 v[36:39], v[208:211], v[184:187], v[36:39]
	v_mfma_f32_16x16x32_bf16 v[32:35], v[216:219], v[184:187], v[32:35]
	v_mfma_f32_16x16x32_bf16 v[20:23], v[208:211], v[192:195], v[20:23]
	v_mfma_f32_16x16x32_bf16 v[16:19], v[216:219], v[192:195], v[16:19]
	v_mfma_f32_16x16x32_bf16 v[4:7], v[208:211], v[200:203], v[4:7]
	v_mfma_f32_16x16x32_bf16 v[0:3], v[216:219], v[200:203], v[0:3]
	s_setprio 0
	s_add_i32 s54, s54, 2
	s_add_u32 s42, s42, 0x100
	s_addc_u32 s43, s43, 0
	s_add_u32 s52, s52, 0x100
	s_addc_u32 s53, s53, 0
	s_cmp_gt_u32 s54, 29
	s_barrier
	s_cbranch_scc0 .LBB0_203
	v_lshl_add_u32 v144, s40, 8, v150
	v_ashrrev_i32_e32 v145, 31, v144
	v_lshl_add_u64 v[148:149], v[144:145], 2, s[14:15]
	v_mov_b32_e32 v145, v224
	v_mov_b32_e32 v204, v225
	v_mov_b32_e32 v205, v226
	v_mov_b32_e32 v206, v227
	v_mov_b32_e32 v207, v228
	v_mov_b32_e32 v208, v229
	v_mov_b32_e32 v209, v230
	v_mov_b32_e32 v210, v231
	v_lshl_or_b32 v156, s34, 7, v152
	v_ashrrev_i32_e32 v157, 31, v156
	v_mov_b64_e32 v[146:147], s[20:21]
	v_mad_i64_i32 v[160:161], s[42:43], v144, s49, v[146:147]
	s_and_b64 vcc, exec, s[4:5]
	s_mov_b32 s34, s22
	s_mov_b32 s40, s24
	s_mov_b64 s[44:45], s[28:29]
	v_mul_f32_e32 v162, v145, v145
	v_mul_f32_e32 v145, 0xbfb8aa3b, v145
	v_mul_f32_e32 v163, v124, v162
	v_mul_f32_e32 v124, v124, v145
	v_exp_f32_e32 v124, v124
	s_nop 0
	v_add_f32_e32 v124, 1.0, v124
	v_rcp_f32_e32 v124, v124
	s_nop 0
	v_mul_f32_e32 v124, v163, v124
	v_mul_f32_e32 v116, v116, v124
	v_mul_f32_e32 v124, v120, v162
	v_mul_f32_e32 v120, v120, v145
	v_exp_f32_e32 v120, v120
	s_nop 0
	v_add_f32_e32 v120, 1.0, v120
	v_rcp_f32_e32 v120, v120
	s_nop 0
	v_mul_f32_e32 v120, v124, v120
	v_mul_f32_e32 v124, v125, v145
	v_exp_f32_e32 v124, v124
	v_mul_f32_e32 v120, v112, v120
	v_mul_f32_e32 v112, v125, v162
	v_add_f32_e32 v124, 1.0, v124
	v_rcp_f32_e32 v124, v124
	s_nop 0
	v_mul_f32_e32 v112, v112, v124
	v_mul_f32_e32 v117, v117, v112
	v_mul_f32_e32 v112, v121, v162
	v_mul_f32_e32 v121, v121, v145
	v_exp_f32_e32 v121, v121
	s_nop 0
	v_add_f32_e32 v121, 1.0, v121
	v_rcp_f32_e32 v121, v121
	s_nop 0
	v_mul_f32_e32 v112, v112, v121
	v_mul_f32_e32 v121, v113, v112
	v_mul_f32_e32 v113, v126, v145
	v_exp_f32_e32 v113, v113
	v_mul_f32_e32 v112, v126, v162
	v_add_f32_e32 v113, 1.0, v113
	v_rcp_f32_e32 v113, v113
	s_nop 0
	v_mul_f32_e32 v112, v112, v113
	v_mul_f32_e32 v113, v122, v145
	v_exp_f32_e32 v113, v113
	v_mul_f32_e32 v124, v118, v112
	v_mul_f32_e32 v112, v122, v162
	v_add_f32_e32 v113, 1.0, v113
	v_rcp_f32_e32 v113, v113
	s_nop 0
	v_mul_f32_e32 v112, v112, v113
	v_mul_f32_e32 v113, v127, v145
	v_exp_f32_e32 v113, v113
	v_mul_f32_e32 v122, v114, v112
	v_mul_f32_e32 v112, v127, v162
	v_cvt_pk_bf16_f32 v114, v116, v117
	v_add_f32_e32 v113, 1.0, v113
	v_rcp_f32_e32 v113, v113
	s_nop 0
	v_mul_f32_e32 v112, v112, v113
	v_mul_f32_e32 v113, v123, v145
	v_exp_f32_e32 v113, v113
	v_mul_f32_e32 v125, v119, v112
	v_mul_f32_e32 v112, v123, v162
	v_add_f32_e32 v113, 1.0, v113
	v_rcp_f32_e32 v113, v113
	s_nop 0
	v_mul_f32_e32 v112, v112, v113
	v_mul_f32_e32 v123, v115, v112
	v_lshlrev_b64 v[112:113], 1, v[156:157]
	v_lshl_add_u64 v[118:119], v[160:161], 0, v[112:113]
	v_cvt_pk_bf16_f32 v115, v124, v125
	v_cvt_pk_bf16_f32 v116, v120, v121
	v_cvt_pk_bf16_f32 v117, v122, v123
	global_store_dwordx4 v[118:119], v[114:117], off
	s_nop 1
	v_mov_b32_e32 v116, v204
	s_nop 0
	v_or_b32_e32 v114, 16, v144
	v_mad_i64_i32 v[114:115], s[42:43], v114, s49, v[146:147]
	v_mul_f32_e32 v117, v116, v116
	v_mul_f32_e32 v116, 0xbfb8aa3b, v116
	v_mul_f32_e32 v118, v108, v117
	v_mul_f32_e32 v108, v108, v116
	v_exp_f32_e32 v108, v108
	s_nop 0
	v_add_f32_e32 v108, 1.0, v108
	v_rcp_f32_e32 v108, v108
	s_nop 0
	v_mul_f32_e32 v108, v118, v108
	v_mul_f32_e32 v108, v100, v108
	v_mul_f32_e32 v100, v104, v117
	v_mul_f32_e32 v104, v104, v116
	v_exp_f32_e32 v104, v104
	s_nop 0
	v_add_f32_e32 v104, 1.0, v104
	v_rcp_f32_e32 v104, v104
	s_nop 0
	v_mul_f32_e32 v100, v100, v104
	v_mul_f32_e32 v104, v96, v100
	v_mul_f32_e32 v100, v109, v116
	v_exp_f32_e32 v100, v100
	v_mul_f32_e32 v96, v109, v117
	v_add_f32_e32 v100, 1.0, v100
	v_rcp_f32_e32 v100, v100
	s_nop 0
	v_mul_f32_e32 v96, v96, v100
	v_mul_f32_e32 v96, v101, v96
	v_mul_f32_e32 v101, v105, v116
	v_exp_f32_e32 v101, v101
	v_mul_f32_e32 v100, v105, v117
	v_cvt_pk_bf16_f32 v96, v108, v96
	v_add_f32_e32 v101, 1.0, v101
	v_rcp_f32_e32 v101, v101
	s_nop 0
	v_mul_f32_e32 v100, v100, v101
	v_mul_f32_e32 v105, v97, v100
	v_mul_f32_e32 v100, v110, v116
	v_exp_f32_e32 v100, v100
	v_mul_f32_e32 v101, v106, v116
	v_exp_f32_e32 v101, v101
; __device__ __forceinline__ float fast_rcp(float x) { return __builtin_amdgcn_rcpf(x); }
; __device__ __forceinline__ float fast_exp2(float x) { return __builtin_amdgcn_exp2f(x); }
; __device__ __forceinline__ u32x4 pack8(f32x4 v0, f32x4 v1) { u32x4 w; w.x = cvt_pk_bf16(v0[0], v0[1]); w.y = cvt_pk_bf16(v0[2], v0[3]); w.z = cvt_pk_bf16(v1[0], v1[1]); w.w = cvt_pk_bf16(v1[2], v1[3]); return w; }
;     __device__ __forceinline__ void operator()(const f32x4 (&acc)[2][2][4][2], const Unit& u, int wr, int wc, int fr, int fq) const {
;     ...
; #pragma unroll
;         for (int ai = 0; ai < 2; ++ai)
; #pragma unroll
;             for (int m = 0; m < 4; ++m) { bf16_t* rowp = O + (size_t)(row0 + ai * HALF + m * 16) * DFF + col0;
;                 const float r = rs[row0 + ai * HALF + m * 16], r2 = r * r;
;                 f32x4 h0, h1;
; #pragma unroll
;                 for (int j = 0; j < 4; ++j) {
;                     const float g0 = acc[ai][0][m][0][j], g1 = acc[ai][0][m][1][j];
;                     h0[j] = g0 * r2 * fast_rcp(1.0f + fast_exp2(g0 * (-LOG2E * r))) * acc[ai][1][m][0][j];
;                     h1[j] = g1 * r2 * fast_rcp(1.0f + fast_exp2(g1 * (-LOG2E * r))) * acc[ai][1][m][1][j]; }
;                 *(u32x4*)rowp = pack8(h0, h1); }
	v_mul_f32_e32 v97, v110, v117
	v_add_f32_e32 v100, 1.0, v100
	v_rcp_f32_e32 v100, v100
	v_add_f32_e32 v101, 1.0, v101
	v_rcp_f32_e32 v101, v101
	v_mul_f32_e32 v97, v97, v100
	v_mul_f32_e32 v100, v106, v117
	v_mul_f32_e32 v100, v100, v101
	v_mul_f32_e32 v97, v102, v97
	v_mul_f32_e32 v102, v98, v100
	v_mul_f32_e32 v100, v111, v116
	v_exp_f32_e32 v100, v100
	v_mul_f32_e32 v101, v107, v116
	v_exp_f32_e32 v101, v101
	v_mul_f32_e32 v98, v111, v117
	v_add_f32_e32 v100, 1.0, v100
	v_rcp_f32_e32 v100, v100
	v_add_f32_e32 v101, 1.0, v101
	v_rcp_f32_e32 v101, v101
	v_mul_f32_e32 v98, v98, v100
	v_mul_f32_e32 v100, v107, v117
	v_mul_f32_e32 v100, v100, v101
	v_mul_f32_e32 v98, v103, v98
	v_mul_f32_e32 v99, v99, v100
	v_lshl_add_u64 v[100:101], v[114:115], 0, v[112:113]
	v_cvt_pk_bf16_f32 v97, v97, v98
	v_cvt_pk_bf16_f32 v98, v104, v105
	v_cvt_pk_bf16_f32 v99, v102, v99
	global_store_dwordx4 v[100:101], v[96:99], off
	s_nop 1
	v_mov_b32_e32 v98, v205
	s_nop 0
	v_or_b32_e32 v96, 32, v144
	v_mad_i64_i32 v[96:97], s[42:43], v96, s49, v[146:147]
	v_mul_f32_e32 v99, v98, v98
	v_mul_f32_e32 v98, 0xbfb8aa3b, v98
	v_mul_f32_e32 v100, v92, v99
	v_mul_f32_e32 v92, v92, v98
	v_exp_f32_e32 v92, v92
	s_nop 0
	v_add_f32_e32 v92, 1.0, v92
	v_rcp_f32_e32 v92, v92
	s_nop 0
	v_mul_f32_e32 v92, v100, v92
	v_mul_f32_e32 v92, v84, v92
	v_mul_f32_e32 v84, v88, v99
	v_mul_f32_e32 v88, v88, v98
	v_exp_f32_e32 v88, v88
	s_nop 0
	v_add_f32_e32 v88, 1.0, v88
	v_rcp_f32_e32 v88, v88
	s_nop 0
	v_mul_f32_e32 v84, v84, v88
	v_mul_f32_e32 v88, v80, v84
	v_mul_f32_e32 v84, v93, v98
	v_exp_f32_e32 v84, v84
	v_mul_f32_e32 v80, v93, v99
	v_add_f32_e32 v84, 1.0, v84
	v_rcp_f32_e32 v84, v84
	s_nop 0
	v_mul_f32_e32 v80, v80, v84
	v_mul_f32_e32 v80, v85, v80
	v_mul_f32_e32 v85, v89, v98
	v_exp_f32_e32 v85, v85
	v_mul_f32_e32 v84, v89, v99
	v_cvt_pk_bf16_f32 v80, v92, v80
	v_add_f32_e32 v85, 1.0, v85
	v_rcp_f32_e32 v85, v85
	s_nop 0
	v_mul_f32_e32 v84, v84, v85
	v_mul_f32_e32 v89, v81, v84
	v_mul_f32_e32 v84, v94, v98
	v_exp_f32_e32 v84, v84
	v_mul_f32_e32 v85, v90, v98
	v_exp_f32_e32 v85, v85
	v_mul_f32_e32 v81, v94, v99
	v_add_f32_e32 v84, 1.0, v84
	v_rcp_f32_e32 v84, v84
	v_add_f32_e32 v85, 1.0, v85
	v_rcp_f32_e32 v85, v85
	v_mul_f32_e32 v81, v81, v84
	v_mul_f32_e32 v84, v90, v99
	v_mul_f32_e32 v84, v84, v85
	v_mul_f32_e32 v81, v86, v81
	v_mul_f32_e32 v86, v82, v84
	v_mul_f32_e32 v84, v95, v98
	v_exp_f32_e32 v84, v84
	v_mul_f32_e32 v85, v91, v98
	v_exp_f32_e32 v85, v85
	v_mul_f32_e32 v82, v95, v99
	v_add_f32_e32 v84, 1.0, v84
	v_rcp_f32_e32 v84, v84
	v_add_f32_e32 v85, 1.0, v85
	v_rcp_f32_e32 v85, v85
	v_mul_f32_e32 v82, v82, v84
	v_mul_f32_e32 v84, v91, v99
	v_mul_f32_e32 v84, v84, v85
	v_mul_f32_e32 v82, v87, v82
	v_mul_f32_e32 v83, v83, v84
	v_lshl_add_u64 v[84:85], v[96:97], 0, v[112:113]
	v_cvt_pk_bf16_f32 v81, v81, v82
	v_cvt_pk_bf16_f32 v82, v88, v89
	v_cvt_pk_bf16_f32 v83, v86, v83
	global_store_dwordx4 v[84:85], v[80:83], off
	s_nop 1
	v_mov_b32_e32 v82, v206
	s_nop 0
	v_or_b32_e32 v80, 48, v144
	v_mad_i64_i32 v[80:81], s[42:43], v80, s49, v[146:147]
	v_mul_f32_e32 v83, v82, v82
	v_mul_f32_e32 v82, 0xbfb8aa3b, v82
	v_mul_f32_e32 v84, v76, v83
	v_mul_f32_e32 v76, v76, v82
	v_exp_f32_e32 v76, v76
	s_nop 0
	v_add_f32_e32 v76, 1.0, v76
	v_rcp_f32_e32 v76, v76
	s_nop 0
	v_mul_f32_e32 v76, v84, v76
	v_mul_f32_e32 v76, v68, v76
	v_mul_f32_e32 v68, v72, v83
	v_mul_f32_e32 v72, v72, v82
	v_exp_f32_e32 v72, v72
	s_nop 0
	v_add_f32_e32 v72, 1.0, v72
	v_rcp_f32_e32 v72, v72
	s_nop 0
	v_mul_f32_e32 v68, v68, v72
	v_mul_f32_e32 v72, v64, v68
	v_mul_f32_e32 v68, v77, v82
	v_exp_f32_e32 v68, v68
	v_mul_f32_e32 v64, v77, v83
	v_add_f32_e32 v68, 1.0, v68
	v_rcp_f32_e32 v68, v68
	s_nop 0
	v_mul_f32_e32 v64, v64, v68
	v_mul_f32_e32 v64, v69, v64
	v_mul_f32_e32 v69, v73, v82
	v_exp_f32_e32 v69, v69
	v_mul_f32_e32 v68, v73, v83
	v_cvt_pk_bf16_f32 v64, v76, v64
	v_add_f32_e32 v69, 1.0, v69
	v_rcp_f32_e32 v69, v69
	s_nop 0
	v_mul_f32_e32 v68, v68, v69
	v_mul_f32_e32 v73, v65, v68
	v_mul_f32_e32 v68, v78, v82
	v_exp_f32_e32 v68, v68
	v_mul_f32_e32 v69, v74, v82
	v_exp_f32_e32 v69, v69
	v_mul_f32_e32 v65, v78, v83
	v_add_f32_e32 v68, 1.0, v68
	v_rcp_f32_e32 v68, v68
	v_add_f32_e32 v69, 1.0, v69
	v_rcp_f32_e32 v69, v69
	v_mul_f32_e32 v65, v65, v68
	v_mul_f32_e32 v68, v74, v83
	v_mul_f32_e32 v68, v68, v69
	v_mul_f32_e32 v65, v70, v65
	v_mul_f32_e32 v70, v66, v68
	v_mul_f32_e32 v68, v79, v82
	v_exp_f32_e32 v68, v68
	v_mul_f32_e32 v69, v75, v82
	v_exp_f32_e32 v69, v69
	v_mul_f32_e32 v66, v79, v83
	v_add_f32_e32 v68, 1.0, v68
	v_rcp_f32_e32 v68, v68
	v_add_f32_e32 v69, 1.0, v69
	v_rcp_f32_e32 v69, v69
	v_mul_f32_e32 v66, v66, v68
	v_mul_f32_e32 v68, v75, v83
	v_mul_f32_e32 v68, v68, v69
	v_mul_f32_e32 v66, v71, v66
	v_mul_f32_e32 v67, v67, v68
	v_lshl_add_u64 v[68:69], v[80:81], 0, v[112:113]
	v_cvt_pk_bf16_f32 v65, v65, v66
	v_cvt_pk_bf16_f32 v66, v72, v73
	v_cvt_pk_bf16_f32 v67, v70, v67
	global_store_dwordx4 v[68:69], v[64:67], off
	s_nop 1
	v_mov_b32_e32 v66, v207
	s_nop 0
	v_add_u32_e32 v64, 0x80, v144
	v_mad_i64_i32 v[64:65], s[42:43], v64, s49, v[146:147]
	v_mul_f32_e32 v67, v66, v66
	v_mul_f32_e32 v66, 0xbfb8aa3b, v66
	v_mul_f32_e32 v68, v60, v67
	v_mul_f32_e32 v60, v60, v66
	v_exp_f32_e32 v60, v60
	s_nop 0
	v_add_f32_e32 v60, 1.0, v60
	v_rcp_f32_e32 v60, v60
	s_nop 0
	v_mul_f32_e32 v60, v68, v60
	v_mul_f32_e32 v60, v52, v60
	v_mul_f32_e32 v52, v56, v67
	v_mul_f32_e32 v56, v56, v66
	v_exp_f32_e32 v56, v56
	s_nop 0
	v_add_f32_e32 v56, 1.0, v56
	v_rcp_f32_e32 v56, v56
	s_nop 0
	v_mul_f32_e32 v52, v52, v56
	v_mul_f32_e32 v56, v48, v52
	v_mul_f32_e32 v52, v61, v66
	v_exp_f32_e32 v52, v52
; __device__ __forceinline__ float fast_rcp(float x) { return __builtin_amdgcn_rcpf(x); }
; __device__ __forceinline__ float fast_exp2(float x) { return __builtin_amdgcn_exp2f(x); }
; __device__ __forceinline__ u32x4 pack8(f32x4 v0, f32x4 v1) { u32x4 w; w.x = cvt_pk_bf16(v0[0], v0[1]); w.y = cvt_pk_bf16(v0[2], v0[3]); w.z = cvt_pk_bf16(v1[0], v1[1]); w.w = cvt_pk_bf16(v1[2], v1[3]); return w; }
;     __device__ __forceinline__ void operator()(const f32x4 (&acc)[2][2][4][2], const Unit& u, int wr, int wc, int fr, int fq) const {
;     ...
; #pragma unroll
;         for (int ai = 0; ai < 2; ++ai)
; #pragma unroll
;             for (int m = 0; m < 4; ++m) { bf16_t* rowp = O + (size_t)(row0 + ai * HALF + m * 16) * DFF + col0;
;                 const float r = rs[row0 + ai * HALF + m * 16], r2 = r * r;
;                 f32x4 h0, h1;
; #pragma unroll
;                 for (int j = 0; j < 4; ++j) {
;                     const float g0 = acc[ai][0][m][0][j], g1 = acc[ai][0][m][1][j];
;                     h0[j] = g0 * r2 * fast_rcp(1.0f + fast_exp2(g0 * (-LOG2E * r))) * acc[ai][1][m][0][j];
;                     h1[j] = g1 * r2 * fast_rcp(1.0f + fast_exp2(g1 * (-LOG2E * r))) * acc[ai][1][m][1][j]; }
;                 *(u32x4*)rowp = pack8(h0, h1); }
	v_mul_f32_e32 v48, v61, v67
	v_add_f32_e32 v52, 1.0, v52
	v_rcp_f32_e32 v52, v52
	s_nop 0
	v_mul_f32_e32 v48, v48, v52
	v_mul_f32_e32 v48, v53, v48
	v_mul_f32_e32 v53, v57, v66
	v_exp_f32_e32 v53, v53
	v_mul_f32_e32 v52, v57, v67
	v_cvt_pk_bf16_f32 v48, v60, v48
	v_add_f32_e32 v53, 1.0, v53
	v_rcp_f32_e32 v53, v53
	s_nop 0
	v_mul_f32_e32 v52, v52, v53
	v_mul_f32_e32 v57, v49, v52
	v_mul_f32_e32 v52, v62, v66
	v_exp_f32_e32 v52, v52
	v_mul_f32_e32 v53, v58, v66
	v_exp_f32_e32 v53, v53
	v_mul_f32_e32 v49, v62, v67
	v_add_f32_e32 v52, 1.0, v52
	v_rcp_f32_e32 v52, v52
	v_add_f32_e32 v53, 1.0, v53
	v_rcp_f32_e32 v53, v53
	v_mul_f32_e32 v49, v49, v52
	v_mul_f32_e32 v52, v58, v67
	v_mul_f32_e32 v52, v52, v53
	v_mul_f32_e32 v49, v54, v49
	v_mul_f32_e32 v54, v50, v52
	v_mul_f32_e32 v52, v63, v66
	v_exp_f32_e32 v52, v52
	v_mul_f32_e32 v53, v59, v66
	v_exp_f32_e32 v53, v53
	v_mul_f32_e32 v50, v63, v67
	v_add_f32_e32 v52, 1.0, v52
	v_rcp_f32_e32 v52, v52
	v_add_f32_e32 v53, 1.0, v53
	v_rcp_f32_e32 v53, v53
	v_mul_f32_e32 v50, v50, v52
	v_mul_f32_e32 v52, v59, v67
	v_mul_f32_e32 v52, v52, v53
	v_mul_f32_e32 v50, v55, v50
	v_mul_f32_e32 v51, v51, v52
	v_lshl_add_u64 v[52:53], v[64:65], 0, v[112:113]
	v_cvt_pk_bf16_f32 v49, v49, v50
	v_cvt_pk_bf16_f32 v50, v56, v57
	v_cvt_pk_bf16_f32 v51, v54, v51
	global_store_dwordx4 v[52:53], v[48:51], off
	s_nop 1
	v_mov_b32_e32 v50, v208
	s_nop 0
	v_add_u32_e32 v48, 0x90, v144
	v_mad_i64_i32 v[48:49], s[42:43], v48, s49, v[146:147]
	v_mul_f32_e32 v51, v50, v50
	v_mul_f32_e32 v50, 0xbfb8aa3b, v50
	v_mul_f32_e32 v52, v44, v51
	v_mul_f32_e32 v44, v44, v50
	v_exp_f32_e32 v44, v44
	s_nop 0
	v_add_f32_e32 v44, 1.0, v44
	v_rcp_f32_e32 v44, v44
	s_nop 0
	v_mul_f32_e32 v44, v52, v44
	v_mul_f32_e32 v44, v36, v44
	v_mul_f32_e32 v36, v40, v51
	v_mul_f32_e32 v40, v40, v50
	v_exp_f32_e32 v40, v40
	s_nop 0
	v_add_f32_e32 v40, 1.0, v40
	v_rcp_f32_e32 v40, v40
	s_nop 0
	v_mul_f32_e32 v36, v36, v40
	v_mul_f32_e32 v40, v32, v36
	v_mul_f32_e32 v36, v45, v50
	v_exp_f32_e32 v36, v36
	v_mul_f32_e32 v32, v45, v51
	v_add_f32_e32 v36, 1.0, v36
	v_rcp_f32_e32 v36, v36
	s_nop 0
	v_mul_f32_e32 v32, v32, v36
	v_mul_f32_e32 v32, v37, v32
	v_mul_f32_e32 v37, v41, v50
	v_exp_f32_e32 v37, v37
	v_mul_f32_e32 v36, v41, v51
	v_cvt_pk_bf16_f32 v32, v44, v32
	v_add_f32_e32 v37, 1.0, v37
	v_rcp_f32_e32 v37, v37
	s_nop 0
	v_mul_f32_e32 v36, v36, v37
	v_mul_f32_e32 v41, v33, v36
	v_mul_f32_e32 v36, v46, v50
	v_exp_f32_e32 v36, v36
	v_mul_f32_e32 v37, v42, v50
	v_exp_f32_e32 v37, v37
	v_mul_f32_e32 v33, v46, v51
	v_add_f32_e32 v36, 1.0, v36
	v_rcp_f32_e32 v36, v36
	v_add_f32_e32 v37, 1.0, v37
	v_rcp_f32_e32 v37, v37
	v_mul_f32_e32 v33, v33, v36
	v_mul_f32_e32 v36, v42, v51
	v_mul_f32_e32 v36, v36, v37
	v_mul_f32_e32 v33, v38, v33
	v_mul_f32_e32 v38, v34, v36
	v_mul_f32_e32 v36, v47, v50
	v_exp_f32_e32 v36, v36
	v_mul_f32_e32 v37, v43, v50
	v_exp_f32_e32 v37, v37
	v_mul_f32_e32 v34, v47, v51
	v_add_f32_e32 v36, 1.0, v36
	v_rcp_f32_e32 v36, v36
	v_add_f32_e32 v37, 1.0, v37
	v_rcp_f32_e32 v37, v37
	v_mul_f32_e32 v34, v34, v36
	v_mul_f32_e32 v36, v43, v51
	v_mul_f32_e32 v36, v36, v37
	v_mul_f32_e32 v34, v39, v34
	v_mul_f32_e32 v35, v35, v36
	v_lshl_add_u64 v[36:37], v[48:49], 0, v[112:113]
	v_cvt_pk_bf16_f32 v33, v33, v34
	v_cvt_pk_bf16_f32 v34, v40, v41
	v_cvt_pk_bf16_f32 v35, v38, v35
	global_store_dwordx4 v[36:37], v[32:35], off
	s_nop 1
	v_mov_b32_e32 v34, v209
	s_nop 0
	v_add_u32_e32 v32, 0xa0, v144
	v_mad_i64_i32 v[32:33], s[42:43], v32, s49, v[146:147]
	v_mul_f32_e32 v35, v34, v34
	v_mul_f32_e32 v34, 0xbfb8aa3b, v34
	v_mul_f32_e32 v36, v28, v35
	v_mul_f32_e32 v28, v28, v34
	v_exp_f32_e32 v28, v28
	s_nop 0
	v_add_f32_e32 v28, 1.0, v28
	v_rcp_f32_e32 v28, v28
; __device__ __forceinline__ float fast_rcp(float x) { return __builtin_amdgcn_rcpf(x); }
; __device__ __forceinline__ float fast_exp2(float x) { return __builtin_amdgcn_exp2f(x); }
; #define PG8_WAIT_V(n) asm volatile("s_waitcnt vmcnt(" #n ")" ::: "memory")
; #define PG8_BAR __builtin_amdgcn_s_barrier()
; __device__ __forceinline__ u32x4 pack8(f32x4 v0, f32x4 v1) { u32x4 w; w.x = cvt_pk_bf16(v0[0], v0[1]); w.y = cvt_pk_bf16(v0[2], v0[3]); w.z = cvt_pk_bf16(v1[0], v1[1]); w.w = cvt_pk_bf16(v1[2], v1[3]); return w; }
; template <class Epi>
; __device__ __forceinline__ void gemm_phase(LAS unsigned char* lds, const Gemm g, const StaticOrder& S, const Epi& E) {
;     ...
;         E(acc, cur, wr, wc, fr, fq);
;         if (!has_next) break;
; #pragma unroll
;         for (int a = 0; a < 2; ++a)
; #pragma unroll
;             for (int b = 0; b < 2; ++b)
; #pragma unroll
;                 for (int m = 0; m < 4; ++m)
; #pragma unroll
;                     for (int n = 0; n < 2; ++n) acc[a][b][m][n] = (f32x4){0.f, 0.f, 0.f, 0.f};
;         cur = nxt; cA = nA; cB = nB; ++ui;
;     }
;     PG8_WAIT_V(0);
;     if (wr == 0) PG8_BAR;
;     __device__ __forceinline__ void operator()(const f32x4 (&acc)[2][2][4][2], const Unit& u, int wr, int wc, int fr, int fq) const {
;     ...
; #pragma unroll
;         for (int ai = 0; ai < 2; ++ai)
; #pragma unroll
;             for (int m = 0; m < 4; ++m) { bf16_t* rowp = O + (size_t)(row0 + ai * HALF + m * 16) * DFF + col0;
;                 const float r = rs[row0 + ai * HALF + m * 16], r2 = r * r;
;                 f32x4 h0, h1;
; #pragma unroll
;                 for (int j = 0; j < 4; ++j) {
;                     const float g0 = acc[ai][0][m][0][j], g1 = acc[ai][0][m][1][j];
;                     h0[j] = g0 * r2 * fast_rcp(1.0f + fast_exp2(g0 * (-LOG2E * r))) * acc[ai][1][m][0][j];
;                     h1[j] = g1 * r2 * fast_rcp(1.0f + fast_exp2(g1 * (-LOG2E * r))) * acc[ai][1][m][1][j]; }
;                 *(u32x4*)rowp = pack8(h0, h1); }
	s_nop 0
	v_mul_f32_e32 v28, v36, v28
	v_mul_f32_e32 v28, v20, v28
	v_mul_f32_e32 v20, v24, v35
	v_mul_f32_e32 v24, v24, v34
	v_exp_f32_e32 v24, v24
	s_nop 0
	v_add_f32_e32 v24, 1.0, v24
	v_rcp_f32_e32 v24, v24
	s_nop 0
	v_mul_f32_e32 v20, v20, v24
	v_mul_f32_e32 v24, v16, v20
	v_mul_f32_e32 v20, v29, v34
	v_exp_f32_e32 v20, v20
	v_mul_f32_e32 v16, v29, v35
	v_add_f32_e32 v20, 1.0, v20
	v_rcp_f32_e32 v20, v20
	s_nop 0
	v_mul_f32_e32 v16, v16, v20
	v_mul_f32_e32 v16, v21, v16
	v_mul_f32_e32 v21, v25, v34
	v_exp_f32_e32 v21, v21
	v_mul_f32_e32 v20, v25, v35
	v_cvt_pk_bf16_f32 v16, v28, v16
	v_add_f32_e32 v21, 1.0, v21
	v_rcp_f32_e32 v21, v21
	s_nop 0
	v_mul_f32_e32 v20, v20, v21
	v_mul_f32_e32 v25, v17, v20
	v_mul_f32_e32 v20, v30, v34
	v_exp_f32_e32 v20, v20
	v_mul_f32_e32 v21, v26, v34
	v_exp_f32_e32 v21, v21
	v_mul_f32_e32 v17, v30, v35
	v_add_f32_e32 v20, 1.0, v20
	v_rcp_f32_e32 v20, v20
	v_add_f32_e32 v21, 1.0, v21
	v_rcp_f32_e32 v21, v21
	v_mul_f32_e32 v17, v17, v20
	v_mul_f32_e32 v20, v26, v35
	v_mul_f32_e32 v20, v20, v21
	v_mul_f32_e32 v17, v22, v17
	v_mul_f32_e32 v22, v18, v20
	v_mul_f32_e32 v20, v31, v34
	v_exp_f32_e32 v20, v20
	v_mul_f32_e32 v21, v27, v34
	v_exp_f32_e32 v21, v21
	v_mul_f32_e32 v18, v31, v35
	v_add_f32_e32 v20, 1.0, v20
	v_rcp_f32_e32 v20, v20
	v_add_f32_e32 v21, 1.0, v21
	v_rcp_f32_e32 v21, v21
	v_mul_f32_e32 v18, v18, v20
	v_mul_f32_e32 v20, v27, v35
	v_mul_f32_e32 v20, v20, v21
	v_mul_f32_e32 v18, v23, v18
	v_mul_f32_e32 v19, v19, v20
	v_lshl_add_u64 v[20:21], v[32:33], 0, v[112:113]
	v_cvt_pk_bf16_f32 v17, v17, v18
	v_cvt_pk_bf16_f32 v18, v24, v25
	v_cvt_pk_bf16_f32 v19, v22, v19
	global_store_dwordx4 v[20:21], v[16:19], off
	s_nop 1
	v_mov_b32_e32 v18, v210
	s_nop 0
	v_add_u32_e32 v16, 0xb0, v144
	v_mad_i64_i32 v[16:17], s[42:43], v16, s49, v[146:147]
	s_mov_b64 s[42:43], s[26:27]
	v_mul_f32_e32 v19, v18, v18
	v_mul_f32_e32 v18, 0xbfb8aa3b, v18
	v_mul_f32_e32 v20, v12, v19
	v_mul_f32_e32 v12, v12, v18
	v_exp_f32_e32 v12, v12
	s_nop 0
	v_add_f32_e32 v12, 1.0, v12
	v_rcp_f32_e32 v12, v12
	s_nop 0
	v_mul_f32_e32 v12, v20, v12
	v_mul_f32_e32 v12, v4, v12
	v_mul_f32_e32 v4, v8, v19
	v_mul_f32_e32 v8, v8, v18
	v_exp_f32_e32 v8, v8
	s_nop 0
	v_add_f32_e32 v8, 1.0, v8
	v_rcp_f32_e32 v8, v8
	s_nop 0
	v_mul_f32_e32 v4, v4, v8
	v_mul_f32_e32 v8, v0, v4
	v_mul_f32_e32 v4, v13, v18
	v_exp_f32_e32 v4, v4
	v_mul_f32_e32 v0, v13, v19
	v_add_f32_e32 v4, 1.0, v4
	v_rcp_f32_e32 v4, v4
	s_nop 0
	v_mul_f32_e32 v0, v0, v4
	v_mul_f32_e32 v0, v5, v0
	v_mul_f32_e32 v5, v9, v18
	v_exp_f32_e32 v5, v5
	v_mul_f32_e32 v4, v9, v19
	v_cvt_pk_bf16_f32 v0, v12, v0
	v_add_f32_e32 v5, 1.0, v5
	v_rcp_f32_e32 v5, v5
	s_nop 0
	v_mul_f32_e32 v4, v4, v5
	v_mul_f32_e32 v9, v1, v4
	v_mul_f32_e32 v4, v14, v18
	v_exp_f32_e32 v4, v4
	v_mul_f32_e32 v5, v10, v18
	v_exp_f32_e32 v5, v5
	v_mul_f32_e32 v1, v14, v19
	v_add_f32_e32 v4, 1.0, v4
	v_rcp_f32_e32 v4, v4
	v_add_f32_e32 v5, 1.0, v5
	v_rcp_f32_e32 v5, v5
	v_mul_f32_e32 v1, v1, v4
	v_mul_f32_e32 v4, v10, v19
	v_mul_f32_e32 v4, v4, v5
	v_mul_f32_e32 v1, v6, v1
	v_mul_f32_e32 v6, v2, v4
	v_mul_f32_e32 v4, v15, v18
	v_exp_f32_e32 v4, v4
	v_mul_f32_e32 v5, v11, v18
	v_exp_f32_e32 v5, v5
	v_mul_f32_e32 v2, v15, v19
	v_add_f32_e32 v4, 1.0, v4
	v_rcp_f32_e32 v4, v4
	v_add_f32_e32 v5, 1.0, v5
	v_rcp_f32_e32 v5, v5
	v_mul_f32_e32 v2, v2, v4
	v_mul_f32_e32 v4, v11, v19
	v_mul_f32_e32 v4, v4, v5
	v_mul_f32_e32 v2, v7, v2
	v_mul_f32_e32 v3, v3, v4
	v_lshl_add_u64 v[4:5], v[16:17], 0, v[112:113]
	v_cvt_pk_bf16_f32 v1, v1, v2
	v_cvt_pk_bf16_f32 v2, v8, v9
	v_cvt_pk_bf16_f32 v3, v6, v3
	global_store_dwordx4 v[4:5], v[0:3], off
	s_cbranch_vccz .LBB0_200
	s_waitcnt vmcnt(0)
	s_cmpk_gt_u32 s3, 0xff
	s_cbranch_scc1 .LBB0_207
	s_barrier

; #define PG8_STAGE(bufoff, gbase, voff) do { _Pragma("unroll") for (int _i = 0; _i < 2; ++_i) \
;         __builtin_amdgcn_global_load_lds((const unsigned*)((const char*)(gbase) + (voff)[_i]), (LAS unsigned*)(lds + (bufoff) + ldsw + _i * 8192), 16, 0, 0); } while (0)
; #define PG8_LDA(dst, b, h) do { _Pragma("unroll") for (int m = 0; m < 4; ++m) _Pragma("unroll") for (int k = 0; k < 2; ++k) dst[m][k] = *(const LAS bf16x8*)(lds + PG8_SA(b, h) + aoff + m * 2048 + k * 1024); } while (0)
; #define PG8_LDB(dst, b, h) do { _Pragma("unroll") for (int n = 0; n < 2; ++n) _Pragma("unroll") for (int k = 0; k < 2; ++k) dst[n][k] = *(const LAS bf16x8*)(lds + PG8_SB(b, h) + boff + n * 2048 + k * 1024); } while (0)
; #define PG8_SCHED __builtin_amdgcn_sched_barrier(0)
; template <class Epi>
; __device__ __forceinline__ void gemm_phase(LAS unsigned char* lds, const Gemm g, const StaticOrder& S, const Epi& E) {
;     ...
;         const bool has_next = S.next(ui + 1, nxt);
;         const char* nA = has_next ? (const char*)g.A + (size_t)nxt.pm * tstep : cA; const char* nB = has_next ? (const char*)g.Bt + (size_t)nxt.pn * tstep : cB;
;         for (int t = 0; t < nt; t += 2) {
;             const bool last = (t == nt - 2);
;             const char* a1 = cA + (size_t)(t + 1) * kstep;
;             const char* a2 = last ? nA : cA + (size_t)(t + 2) * kstep; const char* b2 = last ? nB : cB + (size_t)(t + 2) * kstep;
;             const char* a3 = a2 + kstep; const char* b3 = b2 + kstep;
;             PG8_LDB(B0, 0, 0); PG8_SCHED; PG8_LDA(At, 0, 0); PG8_STAGE(PG8_SA(1, 1), a1 + hstep, voffA);
;     ...
; #pragma unroll
;         for (int a = 0; a < 2; ++a)
; #pragma unroll
;             for (int b = 0; b < 2; ++b)
; #pragma unroll
;                 for (int m = 0; m < 4; ++m)
; #pragma unroll
;                     for (int n = 0; n < 2; ++n) acc[a][b][m][n] = (f32x4){0.f, 0.f, 0.f, 0.f};
;         cur = nxt; cA = nA; cB = nB; ++ui;
.LBB0_795:
	s_ashr_i32 s31, s30, 31
	v_cmp_lt_i64_e32 vcc, s[34:35], v[140:141]
	s_lshl_b64 s[34:35], s[30:31], 20
	s_add_u32 s34, s97, s34
	s_addc_u32 s35, s94, s35
	s_and_b64 s[36:37], vcc, exec
	s_cselect_b32 s31, s35, s41
	s_cselect_b32 s54, s34, s40
	s_ashr_i32 s9, s8, 31
	s_lshl_b64 s[36:37], s[8:9], 20
	s_add_u32 s36, s11, s36
	s_addc_u32 s37, s22, s37
	s_and_b64 s[44:45], vcc, exec
	s_cselect_b32 s9, s37, s43
	s_cselect_b32 s55, s36, s42
	s_add_u32 s40, s40, 0x80080
	s_addc_u32 s41, s41, 0
	s_add_u32 s56, s42, 0x100
	v_mov_b32_e32 v0, 0
	s_addc_u32 s57, s43, 0
	s_mov_b32 s58, -2
	v_mov_b32_e32 v1, v0
	v_mov_b32_e32 v2, v0
	v_mov_b32_e32 v3, v0
	v_mov_b32_e32 v4, v0
	v_mov_b32_e32 v5, v0
	v_mov_b32_e32 v6, v0
	v_mov_b32_e32 v7, v0
	v_mov_b32_e32 v16, v0
	v_mov_b32_e32 v17, v0
	v_mov_b32_e32 v18, v0
	v_mov_b32_e32 v19, v0
	v_mov_b32_e32 v20, v0
	v_mov_b32_e32 v21, v0
	v_mov_b32_e32 v22, v0
	v_mov_b32_e32 v23, v0
	v_mov_b32_e32 v32, v0
	v_mov_b32_e32 v33, v0
	v_mov_b32_e32 v34, v0
	v_mov_b32_e32 v35, v0
	v_mov_b32_e32 v36, v0
	v_mov_b32_e32 v37, v0
	v_mov_b32_e32 v38, v0
	v_mov_b32_e32 v39, v0
	v_mov_b32_e32 v48, v0
	v_mov_b32_e32 v49, v0
	v_mov_b32_e32 v50, v0
	v_mov_b32_e32 v51, v0
	v_mov_b32_e32 v52, v0
	v_mov_b32_e32 v53, v0
	v_mov_b32_e32 v54, v0
	v_mov_b32_e32 v55, v0
	v_mov_b32_e32 v8, v0
	v_mov_b32_e32 v9, v0
	v_mov_b32_e32 v10, v0
	v_mov_b32_e32 v11, v0
	v_mov_b32_e32 v12, v0
	v_mov_b32_e32 v13, v0
	v_mov_b32_e32 v14, v0
	v_mov_b32_e32 v15, v0
	v_mov_b32_e32 v24, v0
	v_mov_b32_e32 v25, v0
	v_mov_b32_e32 v26, v0
	v_mov_b32_e32 v27, v0
	v_mov_b32_e32 v28, v0
	v_mov_b32_e32 v29, v0
	v_mov_b32_e32 v30, v0
	v_mov_b32_e32 v31, v0
	v_mov_b32_e32 v40, v0
	v_mov_b32_e32 v41, v0
	v_mov_b32_e32 v42, v0
	v_mov_b32_e32 v43, v0
	v_mov_b32_e32 v44, v0
	v_mov_b32_e32 v45, v0
	v_mov_b32_e32 v46, v0
	v_mov_b32_e32 v47, v0
	v_mov_b32_e32 v56, v0
	v_mov_b32_e32 v57, v0
	v_mov_b32_e32 v58, v0
	v_mov_b32_e32 v59, v0
	v_mov_b32_e32 v60, v0
	v_mov_b32_e32 v61, v0
	v_mov_b32_e32 v62, v0
	v_mov_b32_e32 v63, v0
	v_mov_b32_e32 v64, v0
	v_mov_b32_e32 v65, v0
	v_mov_b32_e32 v66, v0
	v_mov_b32_e32 v67, v0
	v_mov_b32_e32 v68, v0
	v_mov_b32_e32 v69, v0
	v_mov_b32_e32 v70, v0
	v_mov_b32_e32 v71, v0
	v_mov_b32_e32 v80, v0
	v_mov_b32_e32 v81, v0
	v_mov_b32_e32 v82, v0
	v_mov_b32_e32 v83, v0
	v_mov_b32_e32 v84, v0
	v_mov_b32_e32 v85, v0
	v_mov_b32_e32 v86, v0
	v_mov_b32_e32 v87, v0
	v_mov_b32_e32 v96, v0
	v_mov_b32_e32 v97, v0
	v_mov_b32_e32 v98, v0
	v_mov_b32_e32 v99, v0
	v_mov_b32_e32 v100, v0
	v_mov_b32_e32 v101, v0
	v_mov_b32_e32 v102, v0
	v_mov_b32_e32 v103, v0
	v_mov_b32_e32 v112, v0
	v_mov_b32_e32 v113, v0
	v_mov_b32_e32 v114, v0
	v_mov_b32_e32 v115, v0
	v_mov_b32_e32 v116, v0
	v_mov_b32_e32 v117, v0
	v_mov_b32_e32 v118, v0
	v_mov_b32_e32 v119, v0
	v_mov_b32_e32 v72, v0
	v_mov_b32_e32 v73, v0
	v_mov_b32_e32 v74, v0
	v_mov_b32_e32 v75, v0
	v_mov_b32_e32 v76, v0
	v_mov_b32_e32 v77, v0
	v_mov_b32_e32 v78, v0
	v_mov_b32_e32 v79, v0
	v_mov_b32_e32 v88, v0
	v_mov_b32_e32 v89, v0
	v_mov_b32_e32 v90, v0
	v_mov_b32_e32 v91, v0
	v_mov_b32_e32 v92, v0
	v_mov_b32_e32 v93, v0
	v_mov_b32_e32 v94, v0
	v_mov_b32_e32 v95, v0
	v_mov_b32_e32 v104, v0
	v_mov_b32_e32 v105, v0
	v_mov_b32_e32 v106, v0
	v_mov_b32_e32 v107, v0
	v_mov_b32_e32 v108, v0
	v_mov_b32_e32 v109, v0
	v_mov_b32_e32 v110, v0
	v_mov_b32_e32 v111, v0
	v_mov_b32_e32 v120, v0
	v_mov_b32_e32 v121, v0
	v_mov_b32_e32 v122, v0
	v_mov_b32_e32 v123, v0
	v_mov_b32_e32 v124, v0
	v_mov_b32_e32 v125, v0
	v_mov_b32_e32 v126, v0
	v_mov_b32_e32 v127, v0
	v_lshl_add_u32 v144, s38, 8, v152
	v_ashrrev_i32_e32 v145, 31, v144
	v_lshl_add_u64 v[150:151], v[144:145], 2, s[14:15]
	global_load_dword v224, v[150:151], off
	global_load_dword v225, v[150:151], off offset:64
	global_load_dword v226, v[150:151], off offset:128
	global_load_dword v227, v[150:151], off offset:192
	global_load_dword v228, v[150:151], off offset:512
	global_load_dword v229, v[150:151], off offset:576
	global_load_dword v230, v[150:151], off offset:640
	global_load_dword v231, v[150:151], off offset:704
.LBB0_796:
	ds_read_b128 v[144:147], v155
	ds_read_b128 v[148:151], v155 offset:1024
	ds_read_b128 v[160:163], v155 offset:2048
	ds_read_b128 v[164:167], v155 offset:3072
	s_add_u32 s42, s40, 0xfff80080
	s_addc_u32 s43, s41, -1
	s_cmp_eq_u32 s58, 28
	s_cselect_b32 s45, s31, s43
	s_cselect_b32 s44, s54, s42
	s_cselect_b32 s43, s9, s57
	s_cselect_b32 s42, s55, s56
	v_lshl_add_u64 v[200:201], s[40:41], 0, v[136:137]
	s_add_i32 m0, s27, 0xc000
	ds_read_b128 v[168:171], v156
	ds_read_b128 v[172:175], v156 offset:1024
	ds_read_b128 v[176:179], v156 offset:2048
	ds_read_b128 v[180:183], v156 offset:3072
	ds_read_b128 v[184:187], v156 offset:4096
	ds_read_b128 v[188:191], v156 offset:5120
	ds_read_b128 v[192:195], v156 offset:6144
	ds_read_b128 v[196:199], v156 offset:7168
	global_load_lds_dwordx4 v[200:201], off
	v_lshl_add_u64 v[200:201], s[40:41], 0, v[138:139]
	s_add_i32 m0, s27, 0xe000
	s_nop 0
	global_load_lds_dwordx4 v[200:201], off
	s_waitcnt lgkmcnt(8)
	s_barrier
; #define PG8_STAGE(bufoff, gbase, voff) do { _Pragma("unroll") for (int _i = 0; _i < 2; ++_i) \
;         __builtin_amdgcn_global_load_lds((const unsigned*)((const char*)(gbase) + (voff)[_i]), (LAS unsigned*)(lds + (bufoff) + ldsw + _i * 8192), 16, 0, 0); } while (0)
; #define PG8_LDA(dst, b, h) do { _Pragma("unroll") for (int m = 0; m < 4; ++m) _Pragma("unroll") for (int k = 0; k < 2; ++k) dst[m][k] = *(const LAS bf16x8*)(lds + PG8_SA(b, h) + aoff + m * 2048 + k * 1024); } while (0)
; #define PG8_LDB(dst, b, h) do { _Pragma("unroll") for (int n = 0; n < 2; ++n) _Pragma("unroll") for (int k = 0; k < 2; ++k) dst[n][k] = *(const LAS bf16x8*)(lds + PG8_SB(b, h) + boff + n * 2048 + k * 1024); } while (0)
; #define PG8_MMA(ai, bj, At, Bt) do { __builtin_amdgcn_s_setprio(1); _Pragma("unroll") for (int m = 0; m < 4; ++m) _Pragma("unroll") for (int n = 0; n < 2; ++n) _Pragma("unroll") for (int k = 0; k < 2; ++k) \
;         acc[ai][bj][m][n] = __builtin_amdgcn_mfma_f32_16x16x32_bf16(Bt[n][k], At[m][k], acc[ai][bj][m][n], 0, 0, 0); __builtin_amdgcn_s_setprio(0); } while (0)
; #define PG8_WAIT_V(n) asm volatile("s_waitcnt vmcnt(" #n ")" ::: "memory")
; #define PG8_WAIT_L(n) asm volatile("s_waitcnt lgkmcnt(" #n ")" ::: "memory")
; #define PG8_BAR __builtin_amdgcn_s_barrier()
; #define PG8_SCHED __builtin_amdgcn_sched_barrier(0)
; template <class Epi>
; __device__ __forceinline__ void gemm_phase(LAS unsigned char* lds, const Gemm g, const StaticOrder& S, const Epi& E) {
;     ...
;             PG8_WAIT_L(8); PG8_BAR; PG8_WAIT_L(0); PG8_MMA(0, 0, At, B0); PG8_BAR; PG8_SCHED;
;             PG8_LDB(B1, 0, 1); PG8_STAGE(PG8_SB(0, 0), b2, voffB);
;             PG8_BAR; PG8_WAIT_L(0); PG8_MMA(0, 1, At, B1); PG8_BAR;
;             PG8_LDA(At, 0, 1); PG8_STAGE(PG8_SA(0, 0), a2, voffA);
;             PG8_BAR; PG8_WAIT_L(0); PG8_MMA(1, 0, At, B0); PG8_BAR; PG8_SCHED;
;             PG8_STAGE(PG8_SB(0, 1), b2 + hstep, voffB);
;             PG8_WAIT_V(6); PG8_BAR; PG8_MMA(1, 1, At, B1); PG8_BAR;
	s_waitcnt lgkmcnt(0)
	s_setprio 1
	s_waitcnt lgkmcnt(0)
	v_mfma_f32_16x16x32_bf16 v[124:127], v[144:147], v[168:171], v[124:127]
	v_mfma_f32_16x16x32_bf16 v[120:123], v[160:163], v[168:171], v[120:123]
	v_mfma_f32_16x16x32_bf16 v[108:111], v[144:147], v[176:179], v[108:111]
	v_mfma_f32_16x16x32_bf16 v[104:107], v[160:163], v[176:179], v[104:107]
	v_mfma_f32_16x16x32_bf16 v[92:95], v[144:147], v[184:187], v[92:95]
	v_mfma_f32_16x16x32_bf16 v[88:91], v[160:163], v[184:187], v[88:91]
	v_mfma_f32_16x16x32_bf16 v[76:79], v[144:147], v[192:195], v[76:79]
	v_mfma_f32_16x16x32_bf16 v[72:75], v[160:163], v[192:195], v[72:75]
	v_mfma_f32_16x16x32_bf16 v[124:127], v[148:151], v[172:175], v[124:127]
	v_mfma_f32_16x16x32_bf16 v[120:123], v[164:167], v[172:175], v[120:123]
	v_mfma_f32_16x16x32_bf16 v[108:111], v[148:151], v[180:183], v[108:111]
	v_mfma_f32_16x16x32_bf16 v[104:107], v[164:167], v[180:183], v[104:107]
	v_mfma_f32_16x16x32_bf16 v[92:95], v[148:151], v[188:191], v[92:95]
	v_mfma_f32_16x16x32_bf16 v[88:91], v[164:167], v[188:191], v[88:91]
	v_mfma_f32_16x16x32_bf16 v[76:79], v[148:151], v[196:199], v[76:79]
	v_mfma_f32_16x16x32_bf16 v[72:75], v[164:167], v[196:199], v[72:75]
	s_setprio 0
	s_barrier
	s_add_i32 s59, s50, s23
	v_lshl_add_u64 v[216:217], s[42:43], 0, v[132:133]
	s_mov_b32 m0, s59
	ds_read_b128 v[200:203], v157
	ds_read_b128 v[204:207], v157 offset:1024
	ds_read_b128 v[208:211], v157 offset:2048
	ds_read_b128 v[212:215], v157 offset:3072
	global_load_lds_dwordx4 v[216:217], off
	v_lshl_add_u64 v[218:219], s[42:43], 0, v[128:129]
	s_add_i32 m0, s59, 0x2000
	s_nop 0
	global_load_lds_dwordx4 v[218:219], off
	s_barrier
	s_waitcnt lgkmcnt(0)
	s_setprio 1
	s_waitcnt lgkmcnt(0)
	v_mfma_f32_16x16x32_bf16 v[116:119], v[200:203], v[168:171], v[116:119]
	v_mfma_f32_16x16x32_bf16 v[112:115], v[208:211], v[168:171], v[112:115]
	v_mfma_f32_16x16x32_bf16 v[100:103], v[200:203], v[176:179], v[100:103]
	v_mfma_f32_16x16x32_bf16 v[96:99], v[208:211], v[176:179], v[96:99]
	v_mfma_f32_16x16x32_bf16 v[84:87], v[200:203], v[184:187], v[84:87]
	v_mfma_f32_16x16x32_bf16 v[80:83], v[208:211], v[184:187], v[80:83]
	v_mfma_f32_16x16x32_bf16 v[68:71], v[200:203], v[192:195], v[68:71]
	v_mfma_f32_16x16x32_bf16 v[64:67], v[208:211], v[192:195], v[64:67]
	v_mfma_f32_16x16x32_bf16 v[116:119], v[204:207], v[172:175], v[116:119]
	v_mfma_f32_16x16x32_bf16 v[112:115], v[212:215], v[172:175], v[112:115]
	v_mfma_f32_16x16x32_bf16 v[100:103], v[204:207], v[180:183], v[100:103]
	v_mfma_f32_16x16x32_bf16 v[96:99], v[212:215], v[180:183], v[96:99]
	v_mfma_f32_16x16x32_bf16 v[84:87], v[204:207], v[188:191], v[84:87]
	v_mfma_f32_16x16x32_bf16 v[80:83], v[212:215], v[188:191], v[80:83]
	v_mfma_f32_16x16x32_bf16 v[68:71], v[204:207], v[196:199], v[68:71]
	v_mfma_f32_16x16x32_bf16 v[64:67], v[212:215], v[196:199], v[64:67]
	s_setprio 0
	s_mov_b32 m0, s27
	v_lshl_add_u64 v[220:221], s[44:45], 0, v[134:135]
	s_barrier
	ds_read_b128 v[168:171], v156 offset:16384
	ds_read_b128 v[172:175], v156 offset:17408
	ds_read_b128 v[176:179], v156 offset:18432
	ds_read_b128 v[180:183], v156 offset:19456
	ds_read_b128 v[184:187], v156 offset:20480
	ds_read_b128 v[188:191], v156 offset:21504
	ds_read_b128 v[192:195], v156 offset:22528
	ds_read_b128 v[196:199], v156 offset:23552
	global_load_lds_dwordx4 v[220:221], off
	v_lshl_add_u64 v[222:223], s[44:45], 0, v[130:131]
	s_mov_b32 m0, s28
	s_nop 0
	global_load_lds_dwordx4 v[222:223], off
	s_barrier
	s_waitcnt lgkmcnt(0)
	s_setprio 1
	s_waitcnt lgkmcnt(0)
	v_mfma_f32_16x16x32_bf16 v[60:63], v[144:147], v[168:171], v[60:63]
	v_mfma_f32_16x16x32_bf16 v[56:59], v[160:163], v[168:171], v[56:59]
	v_mfma_f32_16x16x32_bf16 v[44:47], v[144:147], v[176:179], v[44:47]
	v_mfma_f32_16x16x32_bf16 v[40:43], v[160:163], v[176:179], v[40:43]
	v_mfma_f32_16x16x32_bf16 v[28:31], v[144:147], v[184:187], v[28:31]
	v_mfma_f32_16x16x32_bf16 v[24:27], v[160:163], v[184:187], v[24:27]
	v_mfma_f32_16x16x32_bf16 v[12:15], v[144:147], v[192:195], v[12:15]
	v_mfma_f32_16x16x32_bf16 v[8:11], v[160:163], v[192:195], v[8:11]
	v_mfma_f32_16x16x32_bf16 v[60:63], v[148:151], v[172:175], v[60:63]
	v_mfma_f32_16x16x32_bf16 v[56:59], v[164:167], v[172:175], v[56:59]
	v_mfma_f32_16x16x32_bf16 v[44:47], v[148:151], v[180:183], v[44:47]
	v_mfma_f32_16x16x32_bf16 v[40:43], v[164:167], v[180:183], v[40:43]
	v_mfma_f32_16x16x32_bf16 v[28:31], v[148:151], v[188:191], v[28:31]
	v_mfma_f32_16x16x32_bf16 v[24:27], v[164:167], v[188:191], v[24:27]
	v_mfma_f32_16x16x32_bf16 v[12:15], v[148:151], v[196:199], v[12:15]
	v_mfma_f32_16x16x32_bf16 v[8:11], v[164:167], v[196:199], v[8:11]
	s_setprio 0
	s_barrier
	s_add_u32 s60, s42, 0x80000
	s_addc_u32 s61, s43, 0
	s_add_i32 s59, s51, s23
	v_lshl_add_u64 v[144:145], s[60:61], 0, v[132:133]
	s_mov_b32 m0, s59
	s_nop 0
	global_load_lds_dwordx4 v[144:145], off
	v_lshl_add_u64 v[144:145], s[60:61], 0, v[128:129]
	s_add_i32 m0, s59, 0x2000
	s_nop 0
	global_load_lds_dwordx4 v[144:145], off
	s_waitcnt vmcnt(6)
	s_barrier
	s_setprio 1
	v_mfma_f32_16x16x32_bf16 v[52:55], v[200:203], v[168:171], v[52:55]
	v_mfma_f32_16x16x32_bf16 v[48:51], v[208:211], v[168:171], v[48:51]
	v_mfma_f32_16x16x32_bf16 v[36:39], v[200:203], v[176:179], v[36:39]
	v_mfma_f32_16x16x32_bf16 v[32:35], v[208:211], v[176:179], v[32:35]
	v_mfma_f32_16x16x32_bf16 v[20:23], v[200:203], v[184:187], v[20:23]
	v_mfma_f32_16x16x32_bf16 v[16:19], v[208:211], v[184:187], v[16:19]
	v_mfma_f32_16x16x32_bf16 v[4:7], v[200:203], v[192:195], v[4:7]
	v_mfma_f32_16x16x32_bf16 v[0:3], v[208:211], v[192:195], v[0:3]
	v_mfma_f32_16x16x32_bf16 v[52:55], v[204:207], v[172:175], v[52:55]
	v_mfma_f32_16x16x32_bf16 v[48:51], v[212:215], v[172:175], v[48:51]
	v_mfma_f32_16x16x32_bf16 v[36:39], v[204:207], v[180:183], v[36:39]
	v_mfma_f32_16x16x32_bf16 v[32:35], v[212:215], v[180:183], v[32:35]
	v_mfma_f32_16x16x32_bf16 v[20:23], v[204:207], v[188:191], v[20:23]
	v_mfma_f32_16x16x32_bf16 v[16:19], v[212:215], v[188:191], v[16:19]
	v_mfma_f32_16x16x32_bf16 v[4:7], v[204:207], v[196:199], v[4:7]
	v_mfma_f32_16x16x32_bf16 v[0:3], v[212:215], v[196:199], v[0:3]
	s_setprio 0
	s_add_i32 s59, 0, 0x18000
	v_add_u32_e32 v164, s59, v153
	s_barrier
; #define PG8_STAGE(bufoff, gbase, voff) do { _Pragma("unroll") for (int _i = 0; _i < 2; ++_i) \
;         __builtin_amdgcn_global_load_lds((const unsigned*)((const char*)(gbase) + (voff)[_i]), (LAS unsigned*)(lds + (bufoff) + ldsw + _i * 8192), 16, 0, 0); } while (0)
; #define PG8_LDA(dst, b, h) do { _Pragma("unroll") for (int m = 0; m < 4; ++m) _Pragma("unroll") for (int k = 0; k < 2; ++k) dst[m][k] = *(const LAS bf16x8*)(lds + PG8_SA(b, h) + aoff + m * 2048 + k * 1024); } while (0)
; #define PG8_LDB(dst, b, h) do { _Pragma("unroll") for (int n = 0; n < 2; ++n) _Pragma("unroll") for (int k = 0; k < 2; ++k) dst[n][k] = *(const LAS bf16x8*)(lds + PG8_SB(b, h) + boff + n * 2048 + k * 1024); } while (0)
; #define PG8_MMA(ai, bj, At, Bt) do { __builtin_amdgcn_s_setprio(1); _Pragma("unroll") for (int m = 0; m < 4; ++m) _Pragma("unroll") for (int n = 0; n < 2; ++n) _Pragma("unroll") for (int k = 0; k < 2; ++k) \
;         acc[ai][bj][m][n] = __builtin_amdgcn_mfma_f32_16x16x32_bf16(Bt[n][k], At[m][k], acc[ai][bj][m][n], 0, 0, 0); __builtin_amdgcn_s_setprio(0); } while (0)
; #define PG8_WAIT_L(n) asm volatile("s_waitcnt lgkmcnt(" #n ")" ::: "memory")
; #define PG8_BAR __builtin_amdgcn_s_barrier()
; #define PG8_SCHED __builtin_amdgcn_sched_barrier(0)
; template <class Epi>
; __device__ __forceinline__ void gemm_phase(LAS unsigned char* lds, const Gemm g, const StaticOrder& S, const Epi& E) {
;     ...
;             PG8_LDB(B0, 1, 0); PG8_SCHED; PG8_LDA(At, 1, 0); PG8_STAGE(PG8_SA(0, 1), a2 + hstep, voffA);
;             PG8_WAIT_L(8); PG8_BAR; PG8_WAIT_L(0); PG8_MMA(0, 0, At, B0); PG8_BAR; PG8_SCHED;
;             PG8_LDB(B1, 1, 1); PG8_STAGE(PG8_SB(1, 0), b3, voffB);
;             PG8_BAR; PG8_WAIT_L(0); PG8_MMA(0, 1, At, B1); PG8_BAR;
;             PG8_LDA(At, 1, 1); PG8_STAGE(PG8_SA(1, 0), a3, voffA);
;             PG8_BAR; PG8_WAIT_L(0); PG8_MMA(1, 0, At, B0); PG8_BAR; PG8_SCHED;
;             PG8_STAGE(PG8_SB(1, 1), b3 + hstep, voffB);
	ds_read_b128 v[144:147], v164
	ds_read_b128 v[148:151], v164 offset:1024
	ds_read_b128 v[160:163], v164 offset:2048
	ds_read_b128 v[164:167], v164 offset:3072
	s_add_u32 s44, s44, 0x80000
	s_addc_u32 s45, s45, 0
	s_mov_b32 m0, s29
	v_lshl_add_u64 v[200:201], s[44:45], 0, v[134:135]
	ds_read_b128 v[168:171], v156 offset:32768
	ds_read_b128 v[172:175], v156 offset:33792
	ds_read_b128 v[176:179], v156 offset:34816
	ds_read_b128 v[180:183], v156 offset:35840
	ds_read_b128 v[184:187], v156 offset:36864
	ds_read_b128 v[188:191], v156 offset:37888
	ds_read_b128 v[192:195], v156 offset:38912
	ds_read_b128 v[196:199], v156 offset:39936
	global_load_lds_dwordx4 v[200:201], off
	v_lshl_add_u64 v[200:201], s[44:45], 0, v[130:131]
	s_mov_b32 m0, s33
	s_nop 0
	global_load_lds_dwordx4 v[200:201], off
	s_waitcnt lgkmcnt(8)
	s_barrier
	s_waitcnt lgkmcnt(0)
	s_setprio 1
	s_waitcnt lgkmcnt(0)
	v_mfma_f32_16x16x32_bf16 v[124:127], v[144:147], v[168:171], v[124:127]
	v_mfma_f32_16x16x32_bf16 v[120:123], v[160:163], v[168:171], v[120:123]
	v_mfma_f32_16x16x32_bf16 v[108:111], v[144:147], v[176:179], v[108:111]
	v_mfma_f32_16x16x32_bf16 v[104:107], v[160:163], v[176:179], v[104:107]
	v_mfma_f32_16x16x32_bf16 v[92:95], v[144:147], v[184:187], v[92:95]
	v_mfma_f32_16x16x32_bf16 v[88:91], v[160:163], v[184:187], v[88:91]
	v_mfma_f32_16x16x32_bf16 v[76:79], v[144:147], v[192:195], v[76:79]
	v_mfma_f32_16x16x32_bf16 v[72:75], v[160:163], v[192:195], v[72:75]
	v_mfma_f32_16x16x32_bf16 v[124:127], v[148:151], v[172:175], v[124:127]
	v_mfma_f32_16x16x32_bf16 v[120:123], v[164:167], v[172:175], v[120:123]
	v_mfma_f32_16x16x32_bf16 v[108:111], v[148:151], v[180:183], v[108:111]
	v_mfma_f32_16x16x32_bf16 v[104:107], v[164:167], v[180:183], v[104:107]
	v_mfma_f32_16x16x32_bf16 v[92:95], v[148:151], v[188:191], v[92:95]
	v_mfma_f32_16x16x32_bf16 v[88:91], v[164:167], v[188:191], v[88:91]
	v_mfma_f32_16x16x32_bf16 v[76:79], v[148:151], v[196:199], v[76:79]
	v_mfma_f32_16x16x32_bf16 v[72:75], v[164:167], v[196:199], v[72:75]
	s_setprio 0
	s_barrier
	s_add_i32 s44, 0, 0x1c000
	s_add_i32 s45, s59, s23
	v_add_u32_e32 v212, s44, v153
	v_lshl_add_u64 v[216:217], v[216:217], 0, s[2:3]
	s_mov_b32 m0, s45
	ds_read_b128 v[200:203], v212
	ds_read_b128 v[204:207], v212 offset:1024
	ds_read_b128 v[208:211], v212 offset:2048
	ds_read_b128 v[212:215], v212 offset:3072
	global_load_lds_dwordx4 v[216:217], off
	v_lshl_add_u64 v[216:217], v[218:219], 0, s[2:3]
	s_add_i32 m0, s45, 0x2000
	s_nop 0
	global_load_lds_dwordx4 v[216:217], off
	s_barrier
	s_waitcnt lgkmcnt(0)
	s_setprio 1
	s_waitcnt lgkmcnt(0)
	v_mfma_f32_16x16x32_bf16 v[116:119], v[200:203], v[168:171], v[116:119]
	v_mfma_f32_16x16x32_bf16 v[112:115], v[208:211], v[168:171], v[112:115]
	v_mfma_f32_16x16x32_bf16 v[100:103], v[200:203], v[176:179], v[100:103]
	v_mfma_f32_16x16x32_bf16 v[96:99], v[208:211], v[176:179], v[96:99]
	v_mfma_f32_16x16x32_bf16 v[84:87], v[200:203], v[184:187], v[84:87]
	v_mfma_f32_16x16x32_bf16 v[80:83], v[208:211], v[184:187], v[80:83]
	v_mfma_f32_16x16x32_bf16 v[68:71], v[200:203], v[192:195], v[68:71]
	v_mfma_f32_16x16x32_bf16 v[64:67], v[208:211], v[192:195], v[64:67]
	v_mfma_f32_16x16x32_bf16 v[116:119], v[204:207], v[172:175], v[116:119]
	v_mfma_f32_16x16x32_bf16 v[112:115], v[212:215], v[172:175], v[112:115]
	v_mfma_f32_16x16x32_bf16 v[100:103], v[204:207], v[180:183], v[100:103]
	v_mfma_f32_16x16x32_bf16 v[96:99], v[212:215], v[180:183], v[96:99]
	v_mfma_f32_16x16x32_bf16 v[84:87], v[204:207], v[188:191], v[84:87]
	v_mfma_f32_16x16x32_bf16 v[80:83], v[212:215], v[188:191], v[80:83]
	v_mfma_f32_16x16x32_bf16 v[68:71], v[204:207], v[196:199], v[68:71]
	v_mfma_f32_16x16x32_bf16 v[64:67], v[212:215], v[196:199], v[64:67]
	s_setprio 0
	s_mov_b32 m0, s46
	v_lshl_add_u64 v[216:217], v[220:221], 0, s[2:3]
	s_barrier
	ds_read_b128 v[168:171], v156 offset:49152
	ds_read_b128 v[172:175], v156 offset:50176
	ds_read_b128 v[176:179], v156 offset:51200
	ds_read_b128 v[180:183], v156 offset:52224
	ds_read_b128 v[184:187], v156 offset:53248
	ds_read_b128 v[188:191], v156 offset:54272
	ds_read_b128 v[192:195], v156 offset:55296
	ds_read_b128 v[196:199], v156 offset:56320
	global_load_lds_dwordx4 v[216:217], off
	v_lshl_add_u64 v[216:217], v[222:223], 0, s[2:3]
	s_mov_b32 m0, s47
	s_nop 0
	global_load_lds_dwordx4 v[216:217], off
	s_barrier
	s_waitcnt lgkmcnt(0)
	s_setprio 1
	s_waitcnt lgkmcnt(0)
	v_mfma_f32_16x16x32_bf16 v[60:63], v[144:147], v[168:171], v[60:63]
	v_mfma_f32_16x16x32_bf16 v[56:59], v[160:163], v[168:171], v[56:59]
	v_mfma_f32_16x16x32_bf16 v[44:47], v[144:147], v[176:179], v[44:47]
	v_mfma_f32_16x16x32_bf16 v[40:43], v[160:163], v[176:179], v[40:43]
	v_mfma_f32_16x16x32_bf16 v[28:31], v[144:147], v[184:187], v[28:31]
	v_mfma_f32_16x16x32_bf16 v[24:27], v[160:163], v[184:187], v[24:27]
	v_mfma_f32_16x16x32_bf16 v[12:15], v[144:147], v[192:195], v[12:15]
	v_mfma_f32_16x16x32_bf16 v[8:11], v[160:163], v[192:195], v[8:11]
	v_mfma_f32_16x16x32_bf16 v[60:63], v[148:151], v[172:175], v[60:63]
	v_mfma_f32_16x16x32_bf16 v[56:59], v[164:167], v[172:175], v[56:59]
	v_mfma_f32_16x16x32_bf16 v[44:47], v[148:151], v[180:183], v[44:47]
	v_mfma_f32_16x16x32_bf16 v[40:43], v[164:167], v[180:183], v[40:43]
	v_mfma_f32_16x16x32_bf16 v[28:31], v[148:151], v[188:191], v[28:31]
	v_mfma_f32_16x16x32_bf16 v[24:27], v[164:167], v[188:191], v[24:27]
	v_mfma_f32_16x16x32_bf16 v[12:15], v[148:151], v[196:199], v[12:15]
	v_mfma_f32_16x16x32_bf16 v[8:11], v[164:167], v[196:199], v[8:11]
	s_setprio 0
	s_barrier
; __device__ __forceinline__ float fast_rcp(float x) { return __builtin_amdgcn_rcpf(x); }
; __device__ __forceinline__ float fast_exp2(float x) { return __builtin_amdgcn_exp2f(x); }
; #define PG8_MMA(ai, bj, At, Bt) do { __builtin_amdgcn_s_setprio(1); _Pragma("unroll") for (int m = 0; m < 4; ++m) _Pragma("unroll") for (int n = 0; n < 2; ++n) _Pragma("unroll") for (int k = 0; k < 2; ++k) \
;         acc[ai][bj][m][n] = __builtin_amdgcn_mfma_f32_16x16x32_bf16(Bt[n][k], At[m][k], acc[ai][bj][m][n], 0, 0, 0); __builtin_amdgcn_s_setprio(0); } while (0)
; #define PG8_WAIT_V(n) asm volatile("s_waitcnt vmcnt(" #n ")" ::: "memory")
; #define PG8_BAR __builtin_amdgcn_s_barrier()
; __device__ __forceinline__ u32x4 pack8(f32x4 v0, f32x4 v1) { u32x4 w; w.x = cvt_pk_bf16(v0[0], v0[1]); w.y = cvt_pk_bf16(v0[2], v0[3]); w.z = cvt_pk_bf16(v1[0], v1[1]); w.w = cvt_pk_bf16(v1[2], v1[3]); return w; }
; template <class Epi>
; __device__ __forceinline__ void gemm_phase(LAS unsigned char* lds, const Gemm g, const StaticOrder& S, const Epi& E) {
;     ...
;             PG8_WAIT_V(6); PG8_BAR; PG8_MMA(1, 1, At, B1); PG8_BAR;
;         }
;         E(acc, cur, wr, wc, fr, fq);
;     __device__ __forceinline__ void operator()(const f32x4 (&acc)[2][2][4][2], const Unit& u, int wr, int wc, int fr, int fq) const {
;         const int row0 = u.pm * BM + wr * 64 + fr, col0 = u.pn * HALF + wc * 32 + 8 * fq;
; #pragma unroll
;         for (int ai = 0; ai < 2; ++ai)
; #pragma unroll
;             for (int m = 0; m < 4; ++m) { bf16_t* rowp = O + (size_t)(row0 + ai * HALF + m * 16) * DFF + col0;
;                 const float r = rs[row0 + ai * HALF + m * 16], r2 = r * r;
;                 f32x4 h0, h1;
; #pragma unroll
;                 for (int j = 0; j < 4; ++j) {
;                     const float g0 = acc[ai][0][m][0][j], g1 = acc[ai][0][m][1][j];
;                     h0[j] = g0 * r2 * fast_rcp(1.0f + fast_exp2(g0 * (-LOG2E * r))) * acc[ai][1][m][0][j];
;                     h1[j] = g1 * r2 * fast_rcp(1.0f + fast_exp2(g1 * (-LOG2E * r))) * acc[ai][1][m][1][j]; }
;                 *(u32x4*)rowp = pack8(h0, h1); }
	s_add_u32 s42, s42, 0x80080
	s_addc_u32 s43, s43, 0
	s_add_i32 s44, s44, s23
	v_lshl_add_u64 v[144:145], s[42:43], 0, v[132:133]
	s_mov_b32 m0, s44
	s_nop 0
	global_load_lds_dwordx4 v[144:145], off
	v_lshl_add_u64 v[144:145], s[42:43], 0, v[128:129]
	s_add_i32 m0, s44, 0x2000
	s_nop 0
	global_load_lds_dwordx4 v[144:145], off
	s_waitcnt vmcnt(6)
	s_barrier
	s_setprio 1
	v_mfma_f32_16x16x32_bf16 v[52:55], v[200:203], v[168:171], v[52:55]
	v_mfma_f32_16x16x32_bf16 v[48:51], v[208:211], v[168:171], v[48:51]
	v_mfma_f32_16x16x32_bf16 v[36:39], v[200:203], v[176:179], v[36:39]
	v_mfma_f32_16x16x32_bf16 v[32:35], v[208:211], v[176:179], v[32:35]
	v_mfma_f32_16x16x32_bf16 v[20:23], v[200:203], v[184:187], v[20:23]
	v_mfma_f32_16x16x32_bf16 v[16:19], v[208:211], v[184:187], v[16:19]
	v_mfma_f32_16x16x32_bf16 v[4:7], v[200:203], v[192:195], v[4:7]
	v_mfma_f32_16x16x32_bf16 v[0:3], v[208:211], v[192:195], v[0:3]
	v_mfma_f32_16x16x32_bf16 v[52:55], v[204:207], v[172:175], v[52:55]
	v_mfma_f32_16x16x32_bf16 v[48:51], v[212:215], v[172:175], v[48:51]
	v_mfma_f32_16x16x32_bf16 v[36:39], v[204:207], v[180:183], v[36:39]
	v_mfma_f32_16x16x32_bf16 v[32:35], v[212:215], v[180:183], v[32:35]
	v_mfma_f32_16x16x32_bf16 v[20:23], v[204:207], v[188:191], v[20:23]
	v_mfma_f32_16x16x32_bf16 v[16:19], v[212:215], v[188:191], v[16:19]
	v_mfma_f32_16x16x32_bf16 v[4:7], v[204:207], v[196:199], v[4:7]
	v_mfma_f32_16x16x32_bf16 v[0:3], v[212:215], v[196:199], v[0:3]
	s_setprio 0
	s_add_i32 s58, s58, 2
	s_add_u32 s40, s40, 0x100
	s_addc_u32 s41, s41, 0
	s_add_u32 s56, s56, 0x100
	s_addc_u32 s57, s57, 0
	s_cmp_gt_u32 s58, 29
	s_barrier
	s_cbranch_scc0 .LBB0_796
	v_lshl_add_u32 v144, s38, 8, v152
	v_ashrrev_i32_e32 v145, 31, v144
	v_lshl_add_u64 v[150:151], v[144:145], 2, s[14:15]
	v_mov_b32_e32 v145, v224
	v_mov_b32_e32 v204, v225
	v_mov_b32_e32 v205, v226
	v_mov_b32_e32 v206, v227
	v_mov_b32_e32 v207, v228
	v_mov_b32_e32 v208, v229
	v_mov_b32_e32 v209, v230
	v_mov_b32_e32 v210, v231
	v_lshl_or_b32 v148, s53, 7, v154
	v_mov_b64_e32 v[146:147], s[20:21]
	v_ashrrev_i32_e32 v149, 31, v148
	v_mad_i64_i32 v[160:161], s[40:41], v144, s52, v[146:147]
	v_lshlrev_b64 v[148:149], 1, v[148:149]
	v_lshl_add_u64 v[160:161], v[160:161], 0, v[148:149]
	s_and_b64 vcc, exec, s[6:7]
	s_mov_b32 s53, s8
	s_mov_b32 s38, s30
	s_mov_b64 s[42:43], s[36:37]
	v_mul_f32_e32 v162, v145, v145
	v_mul_f32_e32 v145, 0xbfb8aa3b, v145
	v_mul_f32_e32 v163, v124, v162
	v_mul_f32_e32 v164, v120, v162
	v_mul_f32_e32 v120, v120, v145
	v_mul_f32_e32 v165, v125, v162
	v_mul_f32_e32 v125, v125, v145
	v_mul_f32_e32 v166, v121, v162
	v_mul_f32_e32 v121, v121, v145
	v_mul_f32_e32 v167, v126, v162
	v_mul_f32_e32 v126, v126, v145
	v_mul_f32_e32 v168, v122, v162
	v_mul_f32_e32 v122, v122, v145
	v_mul_f32_e32 v169, v127, v162
	v_mul_f32_e32 v127, v127, v145
	v_mul_f32_e32 v162, v123, v162
	v_mul_f32_e32 v123, v123, v145
	v_mul_f32_e32 v124, v124, v145
	v_exp_f32_e32 v120, v120
	v_exp_f32_e32 v125, v125
	v_exp_f32_e32 v121, v121
	v_exp_f32_e32 v126, v126
	v_exp_f32_e32 v122, v122
	v_exp_f32_e32 v127, v127
	v_exp_f32_e32 v123, v123
	v_exp_f32_e32 v124, v124
	v_add_f32_e32 v120, 1.0, v120
	v_add_f32_e32 v125, 1.0, v125
	v_add_f32_e32 v121, 1.0, v121
	v_add_f32_e32 v126, 1.0, v126
	v_add_f32_e32 v122, 1.0, v122
	v_add_f32_e32 v127, 1.0, v127
	v_add_f32_e32 v123, 1.0, v123
	v_add_f32_e32 v124, 1.0, v124
	v_rcp_f32_e32 v120, v120
	v_rcp_f32_e32 v125, v125
	v_rcp_f32_e32 v121, v121
	v_rcp_f32_e32 v126, v126
	v_rcp_f32_e32 v122, v122
	v_rcp_f32_e32 v127, v127
	v_rcp_f32_e32 v123, v123
	v_rcp_f32_e32 v124, v124
	v_mul_f32_e32 v120, v164, v120
	v_mul_f32_e32 v125, v165, v125
	v_mul_f32_e32 v121, v166, v121
	v_mul_f32_e32 v126, v167, v126
	v_mul_f32_e32 v122, v168, v122
	v_mul_f32_e32 v127, v169, v127
	v_mul_f32_e32 v123, v162, v123
	v_mul_f32_e32 v124, v163, v124
	v_mul_f32_e32 v120, v112, v120
	v_mul_f32_e32 v112, v117, v125
	v_mul_f32_e32 v117, v113, v121
	v_mul_f32_e32 v113, v118, v126
	v_mul_f32_e32 v118, v114, v122
	v_mul_f32_e32 v114, v119, v127
	v_mul_f32_e32 v115, v115, v123
	v_mul_f32_e32 v116, v116, v124
	v_cvt_pk_bf16_f32 v112, v116, v112
	v_cvt_pk_bf16_f32 v113, v113, v114
	v_cvt_pk_bf16_f32 v114, v120, v117
	v_cvt_pk_bf16_f32 v115, v118, v115
	global_store_dwordx4 v[160:161], v[112:115], off
	s_nop 1
	v_mov_b32_e32 v114, v204
	s_nop 0
	v_or_b32_e32 v112, 16, v144
	v_mad_i64_i32 v[112:113], s[40:41], v112, s52, v[146:147]
	v_lshl_add_u64 v[112:113], v[112:113], 0, v[148:149]
	v_mul_f32_e32 v115, v114, v114
	v_mul_f32_e32 v114, 0xbfb8aa3b, v114
	v_mul_f32_e32 v116, v108, v115
	v_mul_f32_e32 v117, v104, v115
	v_mul_f32_e32 v104, v104, v114
	v_mul_f32_e32 v118, v109, v115
	v_mul_f32_e32 v109, v109, v114
	v_mul_f32_e32 v119, v105, v115
	v_mul_f32_e32 v105, v105, v114
	v_mul_f32_e32 v120, v110, v115
	v_mul_f32_e32 v110, v110, v114
	v_mul_f32_e32 v121, v106, v115
	v_mul_f32_e32 v106, v106, v114
	v_mul_f32_e32 v122, v111, v115
	v_mul_f32_e32 v111, v111, v114
	v_mul_f32_e32 v115, v107, v115
	v_mul_f32_e32 v107, v107, v114
	v_mul_f32_e32 v108, v108, v114
	v_exp_f32_e32 v104, v104
	v_exp_f32_e32 v109, v109
	v_exp_f32_e32 v105, v105
	v_exp_f32_e32 v110, v110
	v_exp_f32_e32 v106, v106
	v_exp_f32_e32 v111, v111
	v_exp_f32_e32 v107, v107
	v_exp_f32_e32 v108, v108
	v_add_f32_e32 v104, 1.0, v104
	v_add_f32_e32 v109, 1.0, v109
	v_add_f32_e32 v105, 1.0, v105
	v_add_f32_e32 v110, 1.0, v110
	v_add_f32_e32 v106, 1.0, v106
	v_add_f32_e32 v111, 1.0, v111
	v_add_f32_e32 v107, 1.0, v107
	v_add_f32_e32 v108, 1.0, v108
	v_rcp_f32_e32 v104, v104
	v_rcp_f32_e32 v109, v109
	v_rcp_f32_e32 v105, v105
	v_rcp_f32_e32 v110, v110
	v_rcp_f32_e32 v106, v106
; __device__ __forceinline__ float fast_rcp(float x) { return __builtin_amdgcn_rcpf(x); }
; __device__ __forceinline__ float fast_exp2(float x) { return __builtin_amdgcn_exp2f(x); }
; __device__ __forceinline__ u32x4 pack8(f32x4 v0, f32x4 v1) { u32x4 w; w.x = cvt_pk_bf16(v0[0], v0[1]); w.y = cvt_pk_bf16(v0[2], v0[3]); w.z = cvt_pk_bf16(v1[0], v1[1]); w.w = cvt_pk_bf16(v1[2], v1[3]); return w; }
;     __device__ __forceinline__ void operator()(const f32x4 (&acc)[2][2][4][2], const Unit& u, int wr, int wc, int fr, int fq) const {
;         const int row0 = u.pm * BM + wr * 64 + fr, col0 = u.pn * HALF + wc * 32 + 8 * fq;
; #pragma unroll
;         for (int ai = 0; ai < 2; ++ai)
; #pragma unroll
;             for (int m = 0; m < 4; ++m) { bf16_t* rowp = O + (size_t)(row0 + ai * HALF + m * 16) * DFF + col0;
;                 const float r = rs[row0 + ai * HALF + m * 16], r2 = r * r;
;                 f32x4 h0, h1;
; #pragma unroll
;                 for (int j = 0; j < 4; ++j) {
;                     const float g0 = acc[ai][0][m][0][j], g1 = acc[ai][0][m][1][j];
;                     h0[j] = g0 * r2 * fast_rcp(1.0f + fast_exp2(g0 * (-LOG2E * r))) * acc[ai][1][m][0][j];
;                     h1[j] = g1 * r2 * fast_rcp(1.0f + fast_exp2(g1 * (-LOG2E * r))) * acc[ai][1][m][1][j]; }
;                 *(u32x4*)rowp = pack8(h0, h1); }
	v_rcp_f32_e32 v111, v111
	v_rcp_f32_e32 v107, v107
	v_rcp_f32_e32 v108, v108
	v_mul_f32_e32 v104, v117, v104
	v_mul_f32_e32 v109, v118, v109
	v_mul_f32_e32 v105, v119, v105
	v_mul_f32_e32 v110, v120, v110
	v_mul_f32_e32 v106, v121, v106
	v_mul_f32_e32 v111, v122, v111
	v_mul_f32_e32 v107, v115, v107
	v_mul_f32_e32 v108, v116, v108
	v_mul_f32_e32 v104, v96, v104
	v_mul_f32_e32 v96, v101, v109
	v_mul_f32_e32 v101, v97, v105
	v_mul_f32_e32 v97, v102, v110
	v_mul_f32_e32 v102, v98, v106
	v_mul_f32_e32 v98, v103, v111
	v_mul_f32_e32 v99, v99, v107
	v_mul_f32_e32 v100, v100, v108
	v_cvt_pk_bf16_f32 v96, v100, v96
	v_cvt_pk_bf16_f32 v97, v97, v98
	v_cvt_pk_bf16_f32 v98, v104, v101
	v_cvt_pk_bf16_f32 v99, v102, v99
	global_store_dwordx4 v[112:113], v[96:99], off
	s_nop 1
	v_mov_b32_e32 v98, v205
	s_nop 0
	v_or_b32_e32 v96, 32, v144
	v_mad_i64_i32 v[96:97], s[40:41], v96, s52, v[146:147]
	v_lshl_add_u64 v[96:97], v[96:97], 0, v[148:149]
	v_mul_f32_e32 v99, v98, v98
	v_mul_f32_e32 v98, 0xbfb8aa3b, v98
	v_mul_f32_e32 v100, v92, v99
	v_mul_f32_e32 v101, v88, v99
	v_mul_f32_e32 v88, v88, v98
	v_mul_f32_e32 v102, v93, v99
	v_mul_f32_e32 v93, v93, v98
	v_mul_f32_e32 v103, v89, v99
	v_mul_f32_e32 v89, v89, v98
	v_mul_f32_e32 v104, v94, v99
	v_mul_f32_e32 v94, v94, v98
	v_mul_f32_e32 v105, v90, v99
	v_mul_f32_e32 v90, v90, v98
	v_mul_f32_e32 v106, v95, v99
	v_mul_f32_e32 v95, v95, v98
	v_mul_f32_e32 v99, v91, v99
	v_mul_f32_e32 v91, v91, v98
	v_mul_f32_e32 v92, v92, v98
	v_exp_f32_e32 v88, v88
	v_exp_f32_e32 v93, v93
	v_exp_f32_e32 v89, v89
	v_exp_f32_e32 v94, v94
	v_exp_f32_e32 v90, v90
	v_exp_f32_e32 v95, v95
	v_exp_f32_e32 v91, v91
	v_exp_f32_e32 v92, v92
	v_add_f32_e32 v88, 1.0, v88
	v_add_f32_e32 v93, 1.0, v93
	v_add_f32_e32 v89, 1.0, v89
	v_add_f32_e32 v94, 1.0, v94
	v_add_f32_e32 v90, 1.0, v90
	v_add_f32_e32 v95, 1.0, v95
	v_add_f32_e32 v91, 1.0, v91
	v_add_f32_e32 v92, 1.0, v92
	v_rcp_f32_e32 v88, v88
	v_rcp_f32_e32 v93, v93
	v_rcp_f32_e32 v89, v89
	v_rcp_f32_e32 v94, v94
	v_rcp_f32_e32 v90, v90
	v_rcp_f32_e32 v95, v95
	v_rcp_f32_e32 v91, v91
	v_rcp_f32_e32 v92, v92
	v_mul_f32_e32 v88, v101, v88
	v_mul_f32_e32 v93, v102, v93
	v_mul_f32_e32 v89, v103, v89
	v_mul_f32_e32 v94, v104, v94
	v_mul_f32_e32 v90, v105, v90
	v_mul_f32_e32 v95, v106, v95
	v_mul_f32_e32 v91, v99, v91
	v_mul_f32_e32 v92, v100, v92
	v_mul_f32_e32 v88, v80, v88
	v_mul_f32_e32 v80, v85, v93
	v_mul_f32_e32 v85, v81, v89
	v_mul_f32_e32 v81, v86, v94
	v_mul_f32_e32 v86, v82, v90
	v_mul_f32_e32 v82, v87, v95
	v_mul_f32_e32 v83, v83, v91
	v_mul_f32_e32 v84, v84, v92
	v_cvt_pk_bf16_f32 v80, v84, v80
	v_cvt_pk_bf16_f32 v81, v81, v82
	v_cvt_pk_bf16_f32 v82, v88, v85
	v_cvt_pk_bf16_f32 v83, v86, v83
	global_store_dwordx4 v[96:97], v[80:83], off
	s_nop 1
	v_mov_b32_e32 v82, v206
	s_nop 0
	v_or_b32_e32 v80, 48, v144
	v_mad_i64_i32 v[80:81], s[40:41], v80, s52, v[146:147]
	v_lshl_add_u64 v[80:81], v[80:81], 0, v[148:149]
	v_mul_f32_e32 v83, v82, v82
	v_mul_f32_e32 v82, 0xbfb8aa3b, v82
	v_mul_f32_e32 v84, v76, v83
	v_mul_f32_e32 v85, v72, v83
	v_mul_f32_e32 v72, v72, v82
	v_mul_f32_e32 v86, v77, v83
	v_mul_f32_e32 v77, v77, v82
	v_mul_f32_e32 v87, v73, v83
	v_mul_f32_e32 v73, v73, v82
	v_mul_f32_e32 v88, v78, v83
	v_mul_f32_e32 v78, v78, v82
	v_mul_f32_e32 v89, v74, v83
	v_mul_f32_e32 v74, v74, v82
	v_mul_f32_e32 v90, v79, v83
	v_mul_f32_e32 v79, v79, v82
	v_mul_f32_e32 v83, v75, v83
	v_mul_f32_e32 v75, v75, v82
	v_mul_f32_e32 v76, v76, v82
	v_exp_f32_e32 v72, v72
	v_exp_f32_e32 v77, v77
	v_exp_f32_e32 v73, v73
	v_exp_f32_e32 v78, v78
	v_exp_f32_e32 v74, v74
	v_exp_f32_e32 v79, v79
	v_exp_f32_e32 v75, v75
	v_exp_f32_e32 v76, v76
	v_add_f32_e32 v72, 1.0, v72
	v_add_f32_e32 v77, 1.0, v77
	v_add_f32_e32 v73, 1.0, v73
	v_add_f32_e32 v78, 1.0, v78
	v_add_f32_e32 v74, 1.0, v74
	v_add_f32_e32 v79, 1.0, v79
	v_add_f32_e32 v75, 1.0, v75
	v_add_f32_e32 v76, 1.0, v76
	v_rcp_f32_e32 v72, v72
	v_rcp_f32_e32 v77, v77
	v_rcp_f32_e32 v73, v73
	v_rcp_f32_e32 v78, v78
	v_rcp_f32_e32 v74, v74
	v_rcp_f32_e32 v79, v79
	v_rcp_f32_e32 v75, v75
	v_rcp_f32_e32 v76, v76
	v_mul_f32_e32 v72, v85, v72
	v_mul_f32_e32 v77, v86, v77
	v_mul_f32_e32 v73, v87, v73
	v_mul_f32_e32 v78, v88, v78
	v_mul_f32_e32 v74, v89, v74
	v_mul_f32_e32 v79, v90, v79
	v_mul_f32_e32 v75, v83, v75
	v_mul_f32_e32 v76, v84, v76
	v_mul_f32_e32 v72, v64, v72
	v_mul_f32_e32 v64, v69, v77
	v_mul_f32_e32 v69, v65, v73
	v_mul_f32_e32 v65, v70, v78
	v_mul_f32_e32 v70, v66, v74
	v_mul_f32_e32 v66, v71, v79
	v_mul_f32_e32 v67, v67, v75
	v_mul_f32_e32 v68, v68, v76
	v_cvt_pk_bf16_f32 v64, v68, v64
	v_cvt_pk_bf16_f32 v65, v65, v66
	v_cvt_pk_bf16_f32 v66, v72, v69
	v_cvt_pk_bf16_f32 v67, v70, v67
	global_store_dwordx4 v[80:81], v[64:67], off
	s_nop 1
	v_mov_b32_e32 v66, v207
	s_nop 0
	v_add_u32_e32 v64, 0x80, v144
	v_mad_i64_i32 v[64:65], s[40:41], v64, s52, v[146:147]
	v_lshl_add_u64 v[64:65], v[64:65], 0, v[148:149]
	v_mul_f32_e32 v67, v66, v66
	v_mul_f32_e32 v66, 0xbfb8aa3b, v66
	v_mul_f32_e32 v68, v60, v67
	v_mul_f32_e32 v69, v56, v67
	v_mul_f32_e32 v56, v56, v66
	v_mul_f32_e32 v70, v61, v67
	v_mul_f32_e32 v61, v61, v66
	v_mul_f32_e32 v71, v57, v67
	v_mul_f32_e32 v57, v57, v66
	v_mul_f32_e32 v72, v62, v67
	v_mul_f32_e32 v62, v62, v66
	v_mul_f32_e32 v73, v58, v67
	v_mul_f32_e32 v58, v58, v66
	v_mul_f32_e32 v74, v63, v67
	v_mul_f32_e32 v63, v63, v66
	v_mul_f32_e32 v67, v59, v67
	v_mul_f32_e32 v59, v59, v66
	v_mul_f32_e32 v60, v60, v66
	v_exp_f32_e32 v56, v56
	v_exp_f32_e32 v61, v61
	v_exp_f32_e32 v57, v57
	v_exp_f32_e32 v62, v62
	v_exp_f32_e32 v58, v58
	v_exp_f32_e32 v63, v63
	v_exp_f32_e32 v59, v59
	v_exp_f32_e32 v60, v60
	v_add_f32_e32 v56, 1.0, v56
; __device__ __forceinline__ float fast_rcp(float x) { return __builtin_amdgcn_rcpf(x); }
; __device__ __forceinline__ float fast_exp2(float x) { return __builtin_amdgcn_exp2f(x); }
; #define PG8_WAIT_V(n) asm volatile("s_waitcnt vmcnt(" #n ")" ::: "memory")
; #define PG8_BAR __builtin_amdgcn_s_barrier()
; __device__ __forceinline__ u32x4 pack8(f32x4 v0, f32x4 v1) { u32x4 w; w.x = cvt_pk_bf16(v0[0], v0[1]); w.y = cvt_pk_bf16(v0[2], v0[3]); w.z = cvt_pk_bf16(v1[0], v1[1]); w.w = cvt_pk_bf16(v1[2], v1[3]); return w; }
; template <class Epi>
; __device__ __forceinline__ void gemm_phase(LAS unsigned char* lds, const Gemm g, const StaticOrder& S, const Epi& E) {
;     ...
;     PG8_WAIT_V(0);
;     if (wr == 0) PG8_BAR;
;     PG8_BAR;
;     __device__ __forceinline__ void operator()(const f32x4 (&acc)[2][2][4][2], const Unit& u, int wr, int wc, int fr, int fq) const {
;         const int row0 = u.pm * BM + wr * 64 + fr, col0 = u.pn * HALF + wc * 32 + 8 * fq;
; #pragma unroll
;         for (int ai = 0; ai < 2; ++ai)
; #pragma unroll
;             for (int m = 0; m < 4; ++m) { bf16_t* rowp = O + (size_t)(row0 + ai * HALF + m * 16) * DFF + col0;
;                 const float r = rs[row0 + ai * HALF + m * 16], r2 = r * r;
;                 f32x4 h0, h1;
; #pragma unroll
;                 for (int j = 0; j < 4; ++j) {
;                     const float g0 = acc[ai][0][m][0][j], g1 = acc[ai][0][m][1][j];
;                     h0[j] = g0 * r2 * fast_rcp(1.0f + fast_exp2(g0 * (-LOG2E * r))) * acc[ai][1][m][0][j];
;                     h1[j] = g1 * r2 * fast_rcp(1.0f + fast_exp2(g1 * (-LOG2E * r))) * acc[ai][1][m][1][j]; }
;                 *(u32x4*)rowp = pack8(h0, h1); }
	v_add_f32_e32 v61, 1.0, v61
	v_add_f32_e32 v57, 1.0, v57
	v_add_f32_e32 v62, 1.0, v62
	v_add_f32_e32 v58, 1.0, v58
	v_add_f32_e32 v63, 1.0, v63
	v_add_f32_e32 v59, 1.0, v59
	v_add_f32_e32 v60, 1.0, v60
	v_rcp_f32_e32 v56, v56
	v_rcp_f32_e32 v61, v61
	v_rcp_f32_e32 v57, v57
	v_rcp_f32_e32 v62, v62
	v_rcp_f32_e32 v58, v58
	v_rcp_f32_e32 v63, v63
	v_rcp_f32_e32 v59, v59
	v_rcp_f32_e32 v60, v60
	v_mul_f32_e32 v56, v69, v56
	v_mul_f32_e32 v61, v70, v61
	v_mul_f32_e32 v57, v71, v57
	v_mul_f32_e32 v62, v72, v62
	v_mul_f32_e32 v58, v73, v58
	v_mul_f32_e32 v63, v74, v63
	v_mul_f32_e32 v59, v67, v59
	v_mul_f32_e32 v60, v68, v60
	v_mul_f32_e32 v56, v48, v56
	v_mul_f32_e32 v48, v53, v61
	v_mul_f32_e32 v53, v49, v57
	v_mul_f32_e32 v49, v54, v62
	v_mul_f32_e32 v54, v50, v58
	v_mul_f32_e32 v50, v55, v63
	v_mul_f32_e32 v51, v51, v59
	v_mul_f32_e32 v52, v52, v60
	v_cvt_pk_bf16_f32 v48, v52, v48
	v_cvt_pk_bf16_f32 v49, v49, v50
	v_cvt_pk_bf16_f32 v50, v56, v53
	v_cvt_pk_bf16_f32 v51, v54, v51
	global_store_dwordx4 v[64:65], v[48:51], off
	s_nop 1
	v_mov_b32_e32 v50, v208
	s_nop 0
	v_add_u32_e32 v48, 0x90, v144
	v_mad_i64_i32 v[48:49], s[40:41], v48, s52, v[146:147]
	v_lshl_add_u64 v[48:49], v[48:49], 0, v[148:149]
	v_mul_f32_e32 v51, v50, v50
	v_mul_f32_e32 v50, 0xbfb8aa3b, v50
	v_mul_f32_e32 v52, v44, v51
	v_mul_f32_e32 v53, v40, v51
	v_mul_f32_e32 v40, v40, v50
	v_mul_f32_e32 v54, v45, v51
	v_mul_f32_e32 v45, v45, v50
	v_mul_f32_e32 v55, v41, v51
	v_mul_f32_e32 v41, v41, v50
	v_mul_f32_e32 v56, v46, v51
	v_mul_f32_e32 v46, v46, v50
	v_mul_f32_e32 v57, v42, v51
	v_mul_f32_e32 v42, v42, v50
	v_mul_f32_e32 v58, v47, v51
	v_mul_f32_e32 v47, v47, v50
	v_mul_f32_e32 v51, v43, v51
	v_mul_f32_e32 v43, v43, v50
	v_mul_f32_e32 v44, v44, v50
	v_exp_f32_e32 v40, v40
	v_exp_f32_e32 v45, v45
	v_exp_f32_e32 v41, v41
	v_exp_f32_e32 v46, v46
	v_exp_f32_e32 v42, v42
	v_exp_f32_e32 v47, v47
	v_exp_f32_e32 v43, v43
	v_exp_f32_e32 v44, v44
	v_add_f32_e32 v40, 1.0, v40
	v_add_f32_e32 v45, 1.0, v45
	v_add_f32_e32 v41, 1.0, v41
	v_add_f32_e32 v46, 1.0, v46
	v_add_f32_e32 v42, 1.0, v42
	v_add_f32_e32 v47, 1.0, v47
	v_add_f32_e32 v43, 1.0, v43
	v_add_f32_e32 v44, 1.0, v44
	v_rcp_f32_e32 v40, v40
	v_rcp_f32_e32 v45, v45
	v_rcp_f32_e32 v41, v41
	v_rcp_f32_e32 v46, v46
	v_rcp_f32_e32 v42, v42
	v_rcp_f32_e32 v47, v47
	v_rcp_f32_e32 v43, v43
	v_rcp_f32_e32 v44, v44
	v_mul_f32_e32 v40, v53, v40
	v_mul_f32_e32 v45, v54, v45
	v_mul_f32_e32 v41, v55, v41
	v_mul_f32_e32 v46, v56, v46
	v_mul_f32_e32 v42, v57, v42
	v_mul_f32_e32 v47, v58, v47
	v_mul_f32_e32 v43, v51, v43
	v_mul_f32_e32 v44, v52, v44
	v_mul_f32_e32 v40, v32, v40
	v_mul_f32_e32 v32, v37, v45
	v_mul_f32_e32 v37, v33, v41
	v_mul_f32_e32 v33, v38, v46
	v_mul_f32_e32 v38, v34, v42
	v_mul_f32_e32 v34, v39, v47
	v_mul_f32_e32 v35, v35, v43
	v_mul_f32_e32 v36, v36, v44
	v_cvt_pk_bf16_f32 v32, v36, v32
	v_cvt_pk_bf16_f32 v33, v33, v34
	v_cvt_pk_bf16_f32 v34, v40, v37
	v_cvt_pk_bf16_f32 v35, v38, v35
	global_store_dwordx4 v[48:49], v[32:35], off
	s_nop 1
	v_mov_b32_e32 v34, v209
	s_nop 0
	v_add_u32_e32 v32, 0xa0, v144
	v_mad_i64_i32 v[32:33], s[40:41], v32, s52, v[146:147]
	v_lshl_add_u64 v[32:33], v[32:33], 0, v[148:149]
	s_mov_b64 s[40:41], s[34:35]
	v_mul_f32_e32 v35, v34, v34
	v_mul_f32_e32 v34, 0xbfb8aa3b, v34
	v_mul_f32_e32 v36, v28, v35
	v_mul_f32_e32 v37, v24, v35
	v_mul_f32_e32 v24, v24, v34
	v_mul_f32_e32 v38, v29, v35
	v_mul_f32_e32 v29, v29, v34
	v_mul_f32_e32 v39, v25, v35
	v_mul_f32_e32 v25, v25, v34
	v_mul_f32_e32 v40, v30, v35
	v_mul_f32_e32 v30, v30, v34
	v_mul_f32_e32 v41, v26, v35
	v_mul_f32_e32 v26, v26, v34
	v_mul_f32_e32 v42, v31, v35
	v_mul_f32_e32 v31, v31, v34
	v_mul_f32_e32 v35, v27, v35
	v_mul_f32_e32 v27, v27, v34
	v_mul_f32_e32 v28, v28, v34
	v_exp_f32_e32 v24, v24
	v_exp_f32_e32 v29, v29
	v_exp_f32_e32 v25, v25
	v_exp_f32_e32 v30, v30
	v_exp_f32_e32 v26, v26
	v_exp_f32_e32 v31, v31
	v_exp_f32_e32 v27, v27
	v_exp_f32_e32 v28, v28
	v_add_f32_e32 v24, 1.0, v24
	v_add_f32_e32 v29, 1.0, v29
	v_add_f32_e32 v25, 1.0, v25
	v_add_f32_e32 v30, 1.0, v30
	v_add_f32_e32 v26, 1.0, v26
	v_add_f32_e32 v31, 1.0, v31
	v_add_f32_e32 v27, 1.0, v27
	v_add_f32_e32 v28, 1.0, v28
	v_rcp_f32_e32 v24, v24
	v_rcp_f32_e32 v29, v29
	v_rcp_f32_e32 v25, v25
	v_rcp_f32_e32 v30, v30
	v_rcp_f32_e32 v26, v26
	v_rcp_f32_e32 v31, v31
	v_rcp_f32_e32 v27, v27
	v_rcp_f32_e32 v28, v28
	v_mul_f32_e32 v24, v37, v24
	v_mul_f32_e32 v29, v38, v29
	v_mul_f32_e32 v25, v39, v25
	v_mul_f32_e32 v30, v40, v30
	v_mul_f32_e32 v26, v41, v26
	v_mul_f32_e32 v31, v42, v31
	v_mul_f32_e32 v27, v35, v27
	v_mul_f32_e32 v28, v36, v28
	v_mul_f32_e32 v24, v16, v24
	v_mul_f32_e32 v16, v21, v29
	v_mul_f32_e32 v21, v17, v25
	v_mul_f32_e32 v17, v22, v30
	v_mul_f32_e32 v22, v18, v26
	v_mul_f32_e32 v18, v23, v31
	v_mul_f32_e32 v19, v19, v27
	v_mul_f32_e32 v20, v20, v28
	v_cvt_pk_bf16_f32 v16, v20, v16
	v_cvt_pk_bf16_f32 v17, v17, v18
	v_cvt_pk_bf16_f32 v18, v24, v21
	v_cvt_pk_bf16_f32 v19, v22, v19
	global_store_dwordx4 v[32:33], v[16:19], off
	s_nop 1
	v_mov_b32_e32 v18, v210
	s_nop 0
	v_add_u32_e32 v16, 0xb0, v144
	v_mad_i64_i32 v[16:17], s[6:7], v16, s52, v[146:147]
	v_lshl_add_u64 v[16:17], v[16:17], 0, v[148:149]
	v_mul_f32_e32 v19, v18, v18
	v_mul_f32_e32 v18, 0xbfb8aa3b, v18
	v_mul_f32_e32 v20, v12, v19
	v_mul_f32_e32 v21, v8, v19
	v_mul_f32_e32 v8, v8, v18
	v_mul_f32_e32 v22, v13, v19
	v_mul_f32_e32 v13, v13, v18
	v_mul_f32_e32 v23, v9, v19
	v_mul_f32_e32 v9, v9, v18
	v_mul_f32_e32 v24, v14, v19
	v_mul_f32_e32 v14, v14, v18
	v_mul_f32_e32 v25, v10, v19
	v_mul_f32_e32 v10, v10, v18
	v_mul_f32_e32 v26, v15, v19
	v_mul_f32_e32 v15, v15, v18
	v_mul_f32_e32 v19, v11, v19
	v_mul_f32_e32 v11, v11, v18
	v_mul_f32_e32 v12, v12, v18
	v_exp_f32_e32 v8, v8
	v_exp_f32_e32 v13, v13
	v_exp_f32_e32 v9, v9
	v_exp_f32_e32 v14, v14
	v_exp_f32_e32 v10, v10
	v_exp_f32_e32 v15, v15
	v_exp_f32_e32 v11, v11
	v_exp_f32_e32 v12, v12
	v_add_f32_e32 v8, 1.0, v8
	v_add_f32_e32 v13, 1.0, v13
	v_add_f32_e32 v9, 1.0, v9
	v_add_f32_e32 v14, 1.0, v14
	v_add_f32_e32 v10, 1.0, v10
	v_add_f32_e32 v15, 1.0, v15
	v_add_f32_e32 v11, 1.0, v11
	v_add_f32_e32 v12, 1.0, v12
	v_rcp_f32_e32 v8, v8
	v_rcp_f32_e32 v13, v13
	v_rcp_f32_e32 v9, v9
	v_rcp_f32_e32 v14, v14
	v_rcp_f32_e32 v10, v10
	v_rcp_f32_e32 v15, v15
	v_rcp_f32_e32 v11, v11
	v_rcp_f32_e32 v12, v12
	v_mul_f32_e32 v8, v21, v8
	v_mul_f32_e32 v13, v22, v13
	v_mul_f32_e32 v9, v23, v9
	v_mul_f32_e32 v14, v24, v14
	v_mul_f32_e32 v10, v25, v10
	v_mul_f32_e32 v15, v26, v15
	v_mul_f32_e32 v11, v19, v11
	v_mul_f32_e32 v12, v20, v12
	v_mul_f32_e32 v8, v0, v8
	v_mul_f32_e32 v0, v5, v13
	v_mul_f32_e32 v5, v1, v9
	v_mul_f32_e32 v1, v6, v14
	v_mul_f32_e32 v6, v2, v10
	v_mul_f32_e32 v2, v7, v15
	v_mul_f32_e32 v3, v3, v11
	v_mul_f32_e32 v4, v4, v12
	v_cvt_pk_bf16_f32 v0, v4, v0
	v_cvt_pk_bf16_f32 v1, v1, v2
	v_cvt_pk_bf16_f32 v2, v8, v5
	v_cvt_pk_bf16_f32 v3, v6, v3
	global_store_dwordx4 v[16:17], v[0:3], off
	s_cbranch_vccz .LBB0_793
	s_waitcnt vmcnt(0)
	s_cmpk_gt_u32 s10, 0xff
	s_cbranch_scc1 .LBB0_800
	s_barrier
